# ML_Z epilogue: h read and written as 16-byte pieces via permlane16 swap of the f32 factors, scalar tile bases
# speedup vs baseline: 1.2273x; 1.0069x over previous
; #define PG8_STAGE(bufoff, gbase, voff) do { _Pragma("unroll") for (int _i = 0; _i < 2; ++_i) \
;     __builtin_amdgcn_global_load_lds((const unsigned*)((const char*)(gbase) + (voff)[_i]), (PG8_LAS unsigned*)(lds + (bufoff) + ldsw + _i * 8192), 16, 0, 0); } while (0)
; #define PG8_LDA(dst, b, h) do { _Pragma("unroll") for (int m = 0; m < 4; ++m) _Pragma("unroll") for (int k = 0; k < 2; ++k) dst[m][k] = *(const PG8_LAS bf16x8*)(lds + PG8_SA(b, h) + aoff + m * 2048 + k * 1024); } while (0)
; #define PG8_LDB(dst, b, h) do { _Pragma("unroll") for (int n = 0; n < 2; ++n) _Pragma("unroll") for (int k = 0; k < 2; ++k) dst[n][k] = *(const PG8_LAS bf16x8*)(lds + PG8_SB(b, h) + boff + n * 2048 + k * 1024); } while (0)
; #define PG8_BAR __builtin_amdgcn_s_barrier()
; template <class Epi>
; __device__ __forceinline__ void gemm_phase(PG8_LAS unsigned char* lds, const Gemm g, const StaticOrder& S, const Epi& E) {
;     ...
;     for (int t = 0; t < nt; t += 2) {
;       const bool last = (t == nt - 2);
;       const char* a1 = cA + (size_t)(t + 1) * kstep;
;       const char* a2 = last ? nA : cA + (size_t)(t + 2) * kstep; const char* b2 = last ? nB : cB + (size_t)(t + 2) * kstep;
;       const char* a3 = a2 + kstep; const char* b3 = b2 + kstep;
;       PG8_LDB(B0, 0, 0); PG8_SCHED; PG8_LDA(At, 0, 0); PG8_STAGE(PG8_SA(1, 1), a1 + hstep, voffA);
;       PG8_WAIT_L(8); PG8_BAR; PG8_WAIT_L(0); PG8_MMA(0, 0, At, B0); PG8_BAR; PG8_SCHED;
;       PG8_LDB(B1, 0, 1); PG8_STAGE(PG8_SB(0, 0), b2, voffB);
;       PG8_BAR; PG8_WAIT_L(0); PG8_MMA(0, 1, At, B1); PG8_BAR;
;       PG8_LDA(At, 0, 1); PG8_STAGE(PG8_SA(0, 0), a2, voffA);
;       PG8_BAR; PG8_WAIT_L(0); PG8_MMA(1, 0, At, B0); PG8_BAR; PG8_SCHED;
;       PG8_STAGE(PG8_SB(0, 1), b2 + hstep, voffB);
;       PG8_WAIT_V(6); PG8_BAR; PG8_MMA(1, 1, At, B1); PG8_BAR;
;       PG8_LDB(B0, 1, 0); PG8_SCHED; PG8_LDA(At, 1, 0); PG8_STAGE(PG8_SA(0, 1), a2 + hstep, voffA);
;       PG8_WAIT_L(8); PG8_BAR; PG8_WAIT_L(0); PG8_MMA(0, 0, At, B0); PG8_BAR; PG8_SCHED;
;       PG8_LDB(B1, 1, 1); PG8_STAGE(PG8_SB(1, 0), b3, voffB);
;       PG8_BAR; PG8_WAIT_L(0); PG8_MMA(0, 1, At, B1); PG8_BAR;
;       PG8_LDA(At, 1, 1); PG8_STAGE(PG8_SA(1, 0), a3, voffA);
;       PG8_BAR; PG8_WAIT_L(0); PG8_MMA(1, 0, At, B0); PG8_BAR; PG8_SCHED;
;       PG8_STAGE(PG8_SB(1, 1), b3 + hstep, voffB);
;       PG8_WAIT_V(6); PG8_BAR; PG8_MMA(1, 1, At, B1); PG8_BAR;
;     }
.LBB0_1123:
	s_add_u32 s10, s8, 0xfffc0080
	s_addc_u32 s11, s9, -1
	s_add_i32 s64, 0, 0x10000
	v_add_u32_e32 v162, s64, v164
	ds_read_b128 v[154:157], v162
	ds_read_b128 v[158:161], v162 offset:1024
	ds_read_b128 v[188:191], v162 offset:2048
	ds_read_b128 v[192:195], v162 offset:3072
	s_cmp_eq_u32 s63, 12
	s_cselect_b32 s51, s45, s11
	s_cselect_b32 s50, s59, s10
	s_cselect_b32 s11, s43, s62
	s_cselect_b32 s10, s60, s61
	v_lshl_add_u64 v[162:163], s[8:9], 0, v[150:151]
	s_add_i32 m0, s52, 0xc000
	ds_read_b128 v[196:199], v166
	ds_read_b128 v[200:203], v166 offset:1024
	ds_read_b128 v[204:207], v166 offset:2048
	ds_read_b128 v[208:211], v166 offset:3072
	ds_read_b128 v[212:215], v166 offset:4096
	ds_read_b128 v[216:219], v166 offset:5120
	ds_read_b128 v[220:223], v166 offset:6144
	ds_read_b128 v[224:227], v166 offset:7168
	global_load_lds_dwordx4 v[162:163], off
	v_lshl_add_u64 v[162:163], s[8:9], 0, v[152:153]
	s_add_i32 m0, s52, 0xe000
	s_nop 0
	global_load_lds_dwordx4 v[162:163], off
	s_waitcnt lgkmcnt(8)
	s_barrier
	s_waitcnt lgkmcnt(0)
	s_setprio 1
	s_waitcnt lgkmcnt(0)
	v_mfma_f32_16x16x32_bf16 v[126:129], v[154:157], v[196:199], v[126:129]
	v_mfma_f32_16x16x32_bf16 v[122:125], v[188:191], v[196:199], v[122:125]
	v_mfma_f32_16x16x32_bf16 v[110:113], v[154:157], v[204:207], v[110:113]
	v_mfma_f32_16x16x32_bf16 v[106:109], v[188:191], v[204:207], v[106:109]
	v_mfma_f32_16x16x32_bf16 v[94:97], v[154:157], v[212:215], v[94:97]
	v_mfma_f32_16x16x32_bf16 v[90:93], v[188:191], v[212:215], v[90:93]
	v_mfma_f32_16x16x32_bf16 v[78:81], v[154:157], v[220:223], v[78:81]
	v_mfma_f32_16x16x32_bf16 v[74:77], v[188:191], v[220:223], v[74:77]
	v_mfma_f32_16x16x32_bf16 v[126:129], v[158:161], v[200:203], v[126:129]
	v_mfma_f32_16x16x32_bf16 v[122:125], v[192:195], v[200:203], v[122:125]
	v_mfma_f32_16x16x32_bf16 v[110:113], v[158:161], v[208:211], v[110:113]
	v_mfma_f32_16x16x32_bf16 v[106:109], v[192:195], v[208:211], v[106:109]
	v_mfma_f32_16x16x32_bf16 v[94:97], v[158:161], v[216:219], v[94:97]
	v_mfma_f32_16x16x32_bf16 v[90:93], v[192:195], v[216:219], v[90:93]
	v_mfma_f32_16x16x32_bf16 v[78:81], v[158:161], v[224:227], v[78:81]
	v_mfma_f32_16x16x32_bf16 v[74:77], v[192:195], v[224:227], v[74:77]
	s_setprio 0
	s_barrier
	s_add_i32 s66, 0, 0x14000
	v_add_u32_e32 v162, s66, v164
	s_add_i32 s64, s64, s28
	ds_read_b128 v[228:231], v162
	ds_read_b128 v[232:235], v162 offset:1024
	ds_read_b128 v[236:239], v162 offset:2048
	ds_read_b128 v[240:243], v162 offset:3072
	v_lshl_add_u64 v[162:163], s[10:11], 0, v[0:1]
	s_mov_b32 m0, s64
	v_lshl_add_u64 v[178:179], s[10:11], 0, v[148:149]
	global_load_lds_dwordx4 v[162:163], off
	s_add_i32 m0, s64, 0x2000
	s_nop 0
	global_load_lds_dwordx4 v[178:179], off
	s_barrier
	s_waitcnt lgkmcnt(0)
	s_setprio 1
	s_waitcnt lgkmcnt(0)
	v_mfma_f32_16x16x32_bf16 v[118:121], v[228:231], v[196:199], v[118:121]
	v_mfma_f32_16x16x32_bf16 v[114:117], v[236:239], v[196:199], v[114:117]
	v_mfma_f32_16x16x32_bf16 v[102:105], v[228:231], v[204:207], v[102:105]
	v_mfma_f32_16x16x32_bf16 v[98:101], v[236:239], v[204:207], v[98:101]
	v_mfma_f32_16x16x32_bf16 v[86:89], v[228:231], v[212:215], v[86:89]
	v_mfma_f32_16x16x32_bf16 v[82:85], v[236:239], v[212:215], v[82:85]
	v_mfma_f32_16x16x32_bf16 v[70:73], v[228:231], v[220:223], v[70:73]
	v_mfma_f32_16x16x32_bf16 v[66:69], v[236:239], v[220:223], v[66:69]
	v_mfma_f32_16x16x32_bf16 v[118:121], v[232:235], v[200:203], v[118:121]
	v_mfma_f32_16x16x32_bf16 v[114:117], v[240:243], v[200:203], v[114:117]
	v_mfma_f32_16x16x32_bf16 v[102:105], v[232:235], v[208:211], v[102:105]
	v_mfma_f32_16x16x32_bf16 v[98:101], v[240:243], v[208:211], v[98:101]
	v_mfma_f32_16x16x32_bf16 v[86:89], v[232:235], v[216:219], v[86:89]
	v_mfma_f32_16x16x32_bf16 v[82:85], v[240:243], v[216:219], v[82:85]
	v_mfma_f32_16x16x32_bf16 v[70:73], v[232:235], v[224:227], v[70:73]
	v_mfma_f32_16x16x32_bf16 v[66:69], v[240:243], v[224:227], v[66:69]
	s_setprio 0
	s_mov_b32 m0, s52
	v_lshl_add_u64 v[244:245], s[50:51], 0, v[0:1]
	s_barrier
	ds_read_b128 v[196:199], v166 offset:16384
	ds_read_b128 v[200:203], v166 offset:17408
	ds_read_b128 v[204:207], v166 offset:18432
	ds_read_b128 v[208:211], v166 offset:19456
	ds_read_b128 v[212:215], v166 offset:20480
	ds_read_b128 v[216:219], v166 offset:21504
	ds_read_b128 v[220:223], v166 offset:22528
	ds_read_b128 v[224:227], v166 offset:23552
	global_load_lds_dwordx4 v[244:245], off
	v_lshl_add_u64 v[246:247], s[50:51], 0, v[148:149]
	s_mov_b32 m0, s53
	s_nop 0
	global_load_lds_dwordx4 v[246:247], off
	s_barrier
	s_waitcnt lgkmcnt(0)
	s_setprio 1
	s_waitcnt lgkmcnt(0)
	v_mfma_f32_16x16x32_bf16 v[62:65], v[154:157], v[196:199], v[62:65]
	v_mfma_f32_16x16x32_bf16 v[58:61], v[188:191], v[196:199], v[58:61]
	v_mfma_f32_16x16x32_bf16 v[46:49], v[154:157], v[204:207], v[46:49]
	v_mfma_f32_16x16x32_bf16 v[42:45], v[188:191], v[204:207], v[42:45]
	v_mfma_f32_16x16x32_bf16 v[30:33], v[154:157], v[212:215], v[30:33]
	v_mfma_f32_16x16x32_bf16 v[26:29], v[188:191], v[212:215], v[26:29]
	v_mfma_f32_16x16x32_bf16 v[14:17], v[154:157], v[220:223], v[14:17]
	v_mfma_f32_16x16x32_bf16 v[10:13], v[188:191], v[220:223], v[10:13]
	v_mfma_f32_16x16x32_bf16 v[62:65], v[158:161], v[200:203], v[62:65]
	v_mfma_f32_16x16x32_bf16 v[58:61], v[192:195], v[200:203], v[58:61]
	v_mfma_f32_16x16x32_bf16 v[46:49], v[158:161], v[208:211], v[46:49]
	v_mfma_f32_16x16x32_bf16 v[42:45], v[192:195], v[208:211], v[42:45]
	v_mfma_f32_16x16x32_bf16 v[30:33], v[158:161], v[216:219], v[30:33]
	v_mfma_f32_16x16x32_bf16 v[26:29], v[192:195], v[216:219], v[26:29]
	v_mfma_f32_16x16x32_bf16 v[14:17], v[158:161], v[224:227], v[14:17]
	v_mfma_f32_16x16x32_bf16 v[10:13], v[192:195], v[224:227], v[10:13]
	s_setprio 0
	s_barrier
; #define PG8_STAGE(bufoff, gbase, voff) do { _Pragma("unroll") for (int _i = 0; _i < 2; ++_i) \
;     __builtin_amdgcn_global_load_lds((const unsigned*)((const char*)(gbase) + (voff)[_i]), (PG8_LAS unsigned*)(lds + (bufoff) + ldsw + _i * 8192), 16, 0, 0); } while (0)
; #define PG8_LDA(dst, b, h) do { _Pragma("unroll") for (int m = 0; m < 4; ++m) _Pragma("unroll") for (int k = 0; k < 2; ++k) dst[m][k] = *(const PG8_LAS bf16x8*)(lds + PG8_SA(b, h) + aoff + m * 2048 + k * 1024); } while (0)
; #define PG8_LDB(dst, b, h) do { _Pragma("unroll") for (int n = 0; n < 2; ++n) _Pragma("unroll") for (int k = 0; k < 2; ++k) dst[n][k] = *(const PG8_LAS bf16x8*)(lds + PG8_SB(b, h) + boff + n * 2048 + k * 1024); } while (0)
; #define PG8_BAR __builtin_amdgcn_s_barrier()
; template <class Epi>
; __device__ __forceinline__ void gemm_phase(PG8_LAS unsigned char* lds, const Gemm g, const StaticOrder& S, const Epi& E) {
;     ...
;     for (int t = 0; t < nt; t += 2) {
;       const bool last = (t == nt - 2);
;       const char* a1 = cA + (size_t)(t + 1) * kstep;
;       const char* a2 = last ? nA : cA + (size_t)(t + 2) * kstep; const char* b2 = last ? nB : cB + (size_t)(t + 2) * kstep;
;       const char* a3 = a2 + kstep; const char* b3 = b2 + kstep;
;       PG8_LDB(B0, 0, 0); PG8_SCHED; PG8_LDA(At, 0, 0); PG8_STAGE(PG8_SA(1, 1), a1 + hstep, voffA);
;       PG8_WAIT_L(8); PG8_BAR; PG8_WAIT_L(0); PG8_MMA(0, 0, At, B0); PG8_BAR; PG8_SCHED;
;       PG8_LDB(B1, 0, 1); PG8_STAGE(PG8_SB(0, 0), b2, voffB);
;       PG8_BAR; PG8_WAIT_L(0); PG8_MMA(0, 1, At, B1); PG8_BAR;
;       PG8_LDA(At, 0, 1); PG8_STAGE(PG8_SA(0, 0), a2, voffA);
;       PG8_BAR; PG8_WAIT_L(0); PG8_MMA(1, 0, At, B0); PG8_BAR; PG8_SCHED;
;       PG8_STAGE(PG8_SB(0, 1), b2 + hstep, voffB);
;       PG8_WAIT_V(6); PG8_BAR; PG8_MMA(1, 1, At, B1); PG8_BAR;
;       PG8_LDB(B0, 1, 0); PG8_SCHED; PG8_LDA(At, 1, 0); PG8_STAGE(PG8_SA(0, 1), a2 + hstep, voffA);
;       PG8_WAIT_L(8); PG8_BAR; PG8_WAIT_L(0); PG8_MMA(0, 0, At, B0); PG8_BAR; PG8_SCHED;
;       PG8_LDB(B1, 1, 1); PG8_STAGE(PG8_SB(1, 0), b3, voffB);
;       PG8_BAR; PG8_WAIT_L(0); PG8_MMA(0, 1, At, B1); PG8_BAR;
;       PG8_LDA(At, 1, 1); PG8_STAGE(PG8_SA(1, 0), a3, voffA);
;       PG8_BAR; PG8_WAIT_L(0); PG8_MMA(1, 0, At, B0); PG8_BAR; PG8_SCHED;
;       PG8_STAGE(PG8_SB(1, 1), b3 + hstep, voffB);
;       PG8_WAIT_V(6); PG8_BAR; PG8_MMA(1, 1, At, B1); PG8_BAR;
;     }
	s_add_u32 s64, s10, 0x40000
	s_addc_u32 s65, s11, 0
	s_add_i32 s66, s66, s28
	v_lshl_add_u64 v[154:155], s[64:65], 0, v[0:1]
	s_mov_b32 m0, s66
	s_nop 0
	global_load_lds_dwordx4 v[154:155], off
	v_lshl_add_u64 v[154:155], s[64:65], 0, v[148:149]
	s_add_i32 m0, s66, 0x2000
	s_nop 0
	global_load_lds_dwordx4 v[154:155], off
	s_waitcnt vmcnt(6)
	s_barrier
	s_setprio 1
	v_mfma_f32_16x16x32_bf16 v[54:57], v[228:231], v[196:199], v[54:57]
	v_mfma_f32_16x16x32_bf16 v[50:53], v[236:239], v[196:199], v[50:53]
	v_mfma_f32_16x16x32_bf16 v[38:41], v[228:231], v[204:207], v[38:41]
	v_mfma_f32_16x16x32_bf16 v[34:37], v[236:239], v[204:207], v[34:37]
	v_mfma_f32_16x16x32_bf16 v[22:25], v[228:231], v[212:215], v[22:25]
	v_mfma_f32_16x16x32_bf16 v[18:21], v[236:239], v[212:215], v[18:21]
	v_mfma_f32_16x16x32_bf16 v[6:9], v[228:231], v[220:223], v[6:9]
	v_mfma_f32_16x16x32_bf16 v[2:5], v[236:239], v[220:223], v[2:5]
	v_mfma_f32_16x16x32_bf16 v[54:57], v[232:235], v[200:203], v[54:57]
	v_mfma_f32_16x16x32_bf16 v[50:53], v[240:243], v[200:203], v[50:53]
	v_mfma_f32_16x16x32_bf16 v[38:41], v[232:235], v[208:211], v[38:41]
	v_mfma_f32_16x16x32_bf16 v[34:37], v[240:243], v[208:211], v[34:37]
	v_mfma_f32_16x16x32_bf16 v[22:25], v[232:235], v[216:219], v[22:25]
	v_mfma_f32_16x16x32_bf16 v[18:21], v[240:243], v[216:219], v[18:21]
	v_mfma_f32_16x16x32_bf16 v[6:9], v[232:235], v[224:227], v[6:9]
	v_mfma_f32_16x16x32_bf16 v[2:5], v[240:243], v[224:227], v[2:5]
	s_setprio 0
	s_add_i32 s64, 0, 0x18000
	v_add_u32_e32 v167, s64, v164
	s_barrier
	ds_read_b128 v[154:157], v167
	ds_read_b128 v[158:161], v167 offset:1024
	ds_read_b128 v[188:191], v167 offset:2048
	ds_read_b128 v[192:195], v167 offset:3072
	s_add_u32 s50, s50, 0x40000
	s_addc_u32 s51, s51, 0
	s_mov_b32 m0, s54
	v_lshl_add_u64 v[228:229], s[50:51], 0, v[0:1]
	ds_read_b128 v[196:199], v166 offset:32768
	ds_read_b128 v[200:203], v166 offset:33792
	ds_read_b128 v[204:207], v166 offset:34816
	ds_read_b128 v[208:211], v166 offset:35840
	ds_read_b128 v[212:215], v166 offset:36864
	ds_read_b128 v[216:219], v166 offset:37888
	ds_read_b128 v[220:223], v166 offset:38912
	ds_read_b128 v[224:227], v166 offset:39936
	global_load_lds_dwordx4 v[228:229], off
	v_lshl_add_u64 v[228:229], s[50:51], 0, v[148:149]
	s_mov_b32 m0, s55
	s_nop 0
	global_load_lds_dwordx4 v[228:229], off
	s_waitcnt lgkmcnt(8)
	s_barrier
	s_waitcnt lgkmcnt(0)
	s_setprio 1
	s_waitcnt lgkmcnt(0)
	v_mfma_f32_16x16x32_bf16 v[126:129], v[154:157], v[196:199], v[126:129]
	v_mfma_f32_16x16x32_bf16 v[122:125], v[188:191], v[196:199], v[122:125]
	v_mfma_f32_16x16x32_bf16 v[110:113], v[154:157], v[204:207], v[110:113]
	v_mfma_f32_16x16x32_bf16 v[106:109], v[188:191], v[204:207], v[106:109]
	v_mfma_f32_16x16x32_bf16 v[94:97], v[154:157], v[212:215], v[94:97]
	v_mfma_f32_16x16x32_bf16 v[90:93], v[188:191], v[212:215], v[90:93]
	v_mfma_f32_16x16x32_bf16 v[78:81], v[154:157], v[220:223], v[78:81]
	v_mfma_f32_16x16x32_bf16 v[74:77], v[188:191], v[220:223], v[74:77]
	v_mfma_f32_16x16x32_bf16 v[126:129], v[158:161], v[200:203], v[126:129]
	v_mfma_f32_16x16x32_bf16 v[122:125], v[192:195], v[200:203], v[122:125]
	v_mfma_f32_16x16x32_bf16 v[110:113], v[158:161], v[208:211], v[110:113]
	v_mfma_f32_16x16x32_bf16 v[106:109], v[192:195], v[208:211], v[106:109]
	v_mfma_f32_16x16x32_bf16 v[94:97], v[158:161], v[216:219], v[94:97]
	v_mfma_f32_16x16x32_bf16 v[90:93], v[192:195], v[216:219], v[90:93]
	v_mfma_f32_16x16x32_bf16 v[78:81], v[158:161], v[224:227], v[78:81]
	v_mfma_f32_16x16x32_bf16 v[74:77], v[192:195], v[224:227], v[74:77]
	s_setprio 0
	s_barrier
	s_add_i32 s50, 0, 0x1c000
	s_add_i32 s51, s64, s28
	v_add_u32_e32 v167, s50, v164
	v_lshl_add_u64 v[162:163], v[162:163], 0, s[4:5]
	s_mov_b32 m0, s51
	ds_read_b128 v[228:231], v167
	ds_read_b128 v[232:235], v167 offset:1024
	ds_read_b128 v[236:239], v167 offset:2048
	ds_read_b128 v[240:243], v167 offset:3072
	global_load_lds_dwordx4 v[162:163], off
	v_lshl_add_u64 v[162:163], v[178:179], 0, s[4:5]
	s_add_i32 m0, s51, 0x2000
	s_nop 0
	global_load_lds_dwordx4 v[162:163], off
	s_barrier
	s_waitcnt lgkmcnt(0)
	s_setprio 1
	s_waitcnt lgkmcnt(0)
	v_mfma_f32_16x16x32_bf16 v[118:121], v[228:231], v[196:199], v[118:121]
	v_mfma_f32_16x16x32_bf16 v[114:117], v[236:239], v[196:199], v[114:117]
	v_mfma_f32_16x16x32_bf16 v[102:105], v[228:231], v[204:207], v[102:105]
	v_mfma_f32_16x16x32_bf16 v[98:101], v[236:239], v[204:207], v[98:101]
	v_mfma_f32_16x16x32_bf16 v[86:89], v[228:231], v[212:215], v[86:89]
	v_mfma_f32_16x16x32_bf16 v[82:85], v[236:239], v[212:215], v[82:85]
	v_mfma_f32_16x16x32_bf16 v[70:73], v[228:231], v[220:223], v[70:73]
	v_mfma_f32_16x16x32_bf16 v[66:69], v[236:239], v[220:223], v[66:69]
	v_mfma_f32_16x16x32_bf16 v[118:121], v[232:235], v[200:203], v[118:121]
	v_mfma_f32_16x16x32_bf16 v[114:117], v[240:243], v[200:203], v[114:117]
	v_mfma_f32_16x16x32_bf16 v[102:105], v[232:235], v[208:211], v[102:105]
	v_mfma_f32_16x16x32_bf16 v[98:101], v[240:243], v[208:211], v[98:101]
	v_mfma_f32_16x16x32_bf16 v[86:89], v[232:235], v[216:219], v[86:89]
	v_mfma_f32_16x16x32_bf16 v[82:85], v[240:243], v[216:219], v[82:85]
	v_mfma_f32_16x16x32_bf16 v[70:73], v[232:235], v[224:227], v[70:73]
	v_mfma_f32_16x16x32_bf16 v[66:69], v[240:243], v[224:227], v[66:69]
	s_setprio 0
	s_mov_b32 m0, s56
	v_lshl_add_u64 v[162:163], v[244:245], 0, s[4:5]
	s_barrier
	ds_read_b128 v[196:199], v166 offset:49152
	ds_read_b128 v[200:203], v166 offset:50176
	ds_read_b128 v[204:207], v166 offset:51200
	ds_read_b128 v[208:211], v166 offset:52224
	ds_read_b128 v[212:215], v166 offset:53248
	ds_read_b128 v[216:219], v166 offset:54272
	ds_read_b128 v[220:223], v166 offset:55296
	ds_read_b128 v[224:227], v166 offset:56320
	global_load_lds_dwordx4 v[162:163], off
	v_lshl_add_u64 v[162:163], v[246:247], 0, s[4:5]
	s_mov_b32 m0, s57
	s_nop 0
	global_load_lds_dwordx4 v[162:163], off
	s_barrier
; #define PG8_STAGE(bufoff, gbase, voff) do { _Pragma("unroll") for (int _i = 0; _i < 2; ++_i) \
;     __builtin_amdgcn_global_load_lds((const unsigned*)((const char*)(gbase) + (voff)[_i]), (PG8_LAS unsigned*)(lds + (bufoff) + ldsw + _i * 8192), 16, 0, 0); } while (0)
; #define PG8_LDA(dst, b, h) do { _Pragma("unroll") for (int m = 0; m < 4; ++m) _Pragma("unroll") for (int k = 0; k < 2; ++k) dst[m][k] = *(const PG8_LAS bf16x8*)(lds + PG8_SA(b, h) + aoff + m * 2048 + k * 1024); } while (0)
; #define PG8_LDB(dst, b, h) do { _Pragma("unroll") for (int n = 0; n < 2; ++n) _Pragma("unroll") for (int k = 0; k < 2; ++k) dst[n][k] = *(const PG8_LAS bf16x8*)(lds + PG8_SB(b, h) + boff + n * 2048 + k * 1024); } while (0)
; #define PG8_MMA(ai, bj, At, Bt) do { __builtin_amdgcn_s_setprio(1); _Pragma("unroll") for (int m = 0; m < 4; ++m) _Pragma("unroll") for (int n = 0; n < 2; ++n) _Pragma("unroll") for (int k = 0; k < 2; ++k) \
;     acc[ai][bj][m][n] = __builtin_amdgcn_mfma_f32_16x16x32_bf16(Bt[n][k], At[m][k], acc[ai][bj][m][n], 0, 0, 0); __builtin_amdgcn_s_setprio(0); } while (0)
; #define PG8_WAIT_V(n) asm volatile("s_waitcnt vmcnt(" #n ")" ::: "memory")
; #define PG8_WAIT_L(n) asm volatile("s_waitcnt lgkmcnt(" #n ")" ::: "memory")
; #define PG8_BAR __builtin_amdgcn_s_barrier()
; #define PG8_SCHED __builtin_amdgcn_sched_barrier(0)
; template <class Epi>
; __device__ __forceinline__ void gemm_phase(PG8_LAS unsigned char* lds, const Gemm g, const StaticOrder& S, const Epi& E) {
;     ...
;       PG8_WAIT_L(8); PG8_BAR; PG8_WAIT_L(0); PG8_MMA(0, 0, At, B0); PG8_BAR; PG8_SCHED;
;       PG8_LDB(B1, 1, 1); PG8_STAGE(PG8_SB(1, 0), b3, voffB);
;       PG8_BAR; PG8_WAIT_L(0); PG8_MMA(0, 1, At, B1); PG8_BAR;
;       PG8_LDA(At, 1, 1); PG8_STAGE(PG8_SA(1, 0), a3, voffA);
;       PG8_BAR; PG8_WAIT_L(0); PG8_MMA(1, 0, At, B0); PG8_BAR; PG8_SCHED;
;       PG8_STAGE(PG8_SB(1, 1), b3 + hstep, voffB);
;       PG8_WAIT_V(6); PG8_BAR; PG8_MMA(1, 1, At, B1); PG8_BAR;
;     }
	s_waitcnt lgkmcnt(0)
	s_setprio 1
	s_waitcnt lgkmcnt(0)
	v_mfma_f32_16x16x32_bf16 v[62:65], v[154:157], v[196:199], v[62:65]
	v_mfma_f32_16x16x32_bf16 v[58:61], v[188:191], v[196:199], v[58:61]
	v_mfma_f32_16x16x32_bf16 v[46:49], v[154:157], v[204:207], v[46:49]
	v_mfma_f32_16x16x32_bf16 v[42:45], v[188:191], v[204:207], v[42:45]
	v_mfma_f32_16x16x32_bf16 v[30:33], v[154:157], v[212:215], v[30:33]
	v_mfma_f32_16x16x32_bf16 v[26:29], v[188:191], v[212:215], v[26:29]
	v_mfma_f32_16x16x32_bf16 v[14:17], v[154:157], v[220:223], v[14:17]
	v_mfma_f32_16x16x32_bf16 v[10:13], v[188:191], v[220:223], v[10:13]
	v_mfma_f32_16x16x32_bf16 v[62:65], v[158:161], v[200:203], v[62:65]
	v_mfma_f32_16x16x32_bf16 v[58:61], v[192:195], v[200:203], v[58:61]
	v_mfma_f32_16x16x32_bf16 v[46:49], v[158:161], v[208:211], v[46:49]
	v_mfma_f32_16x16x32_bf16 v[42:45], v[192:195], v[208:211], v[42:45]
	v_mfma_f32_16x16x32_bf16 v[30:33], v[158:161], v[216:219], v[30:33]
	v_mfma_f32_16x16x32_bf16 v[26:29], v[192:195], v[216:219], v[26:29]
	v_mfma_f32_16x16x32_bf16 v[14:17], v[158:161], v[224:227], v[14:17]
	v_mfma_f32_16x16x32_bf16 v[10:13], v[192:195], v[224:227], v[10:13]
	s_setprio 0
	s_barrier
	s_add_u32 s10, s10, 0x40080
	s_addc_u32 s11, s11, 0
	s_add_i32 s50, s50, s28
	v_lshl_add_u64 v[154:155], s[10:11], 0, v[0:1]
	s_mov_b32 m0, s50
	s_nop 0
	global_load_lds_dwordx4 v[154:155], off
	v_lshl_add_u64 v[154:155], s[10:11], 0, v[148:149]
	s_add_i32 m0, s50, 0x2000
	s_nop 0
	global_load_lds_dwordx4 v[154:155], off
	s_waitcnt vmcnt(6)
	s_barrier
	s_setprio 1
	v_mfma_f32_16x16x32_bf16 v[54:57], v[228:231], v[196:199], v[54:57]
	v_mfma_f32_16x16x32_bf16 v[50:53], v[236:239], v[196:199], v[50:53]
	v_mfma_f32_16x16x32_bf16 v[38:41], v[228:231], v[204:207], v[38:41]
	v_mfma_f32_16x16x32_bf16 v[34:37], v[236:239], v[204:207], v[34:37]
	v_mfma_f32_16x16x32_bf16 v[22:25], v[228:231], v[212:215], v[22:25]
	v_mfma_f32_16x16x32_bf16 v[18:21], v[236:239], v[212:215], v[18:21]
	v_mfma_f32_16x16x32_bf16 v[6:9], v[228:231], v[220:223], v[6:9]
	v_mfma_f32_16x16x32_bf16 v[2:5], v[236:239], v[220:223], v[2:5]
	v_mfma_f32_16x16x32_bf16 v[54:57], v[232:235], v[200:203], v[54:57]
	v_mfma_f32_16x16x32_bf16 v[50:53], v[240:243], v[200:203], v[50:53]
	v_mfma_f32_16x16x32_bf16 v[38:41], v[232:235], v[208:211], v[38:41]
	v_mfma_f32_16x16x32_bf16 v[34:37], v[240:243], v[208:211], v[34:37]
	v_mfma_f32_16x16x32_bf16 v[22:25], v[232:235], v[216:219], v[22:25]
	v_mfma_f32_16x16x32_bf16 v[18:21], v[240:243], v[216:219], v[18:21]
	v_mfma_f32_16x16x32_bf16 v[6:9], v[232:235], v[224:227], v[6:9]
	v_mfma_f32_16x16x32_bf16 v[2:5], v[240:243], v[224:227], v[2:5]
	s_setprio 0
	s_add_i32 s63, s63, 2
	s_add_u32 s8, s8, 0x100
	s_addc_u32 s9, s9, 0
	s_add_u32 s61, s61, 0x100
	s_addc_u32 s62, s62, 0
	s_cmp_gt_u32 s63, 13
	s_barrier
	s_cbranch_scc0 .LBB0_1123
	v_bfe_u32 v154, v168, 4, 1
	v_mul_u32_u24_e32 v154, 24, v154
	v_lshl_add_u32 v154, v165, 1, v154
	v_lshl_add_u32 v154, v147, 12, v154
	v_lshlrev_b32_e32 v155, 5, v147
	v_lshl_or_b32 v160, s6, 8, v165
	v_lshlrev_b32_e32 v162, 2, v160
	v_mov_b32_e32 v163, 0
	v_lshl_add_u64 v[162:163], v[162:163], 0, s[30:31]
	global_load_dwordx4 v[228:231], v[162:163], off
	global_load_dwordx4 v[232:235], v[162:163], off offset:64
	global_load_dwordx4 v[236:239], v[162:163], off offset:512
	global_load_dwordx4 v[240:243], v[162:163], off offset:576
	v_readlane_b32 s50, v251, 37
	v_readlane_b32 s51, v251, 38
	s_lshl_b32 s8, s7, 13
	s_lshl_b32 s9, s6, 2
	s_add_i32 s8, s8, s9
	s_add_u32 s50, s50, s8
	s_addc_u32 s51, s51, 0
	s_lshl_b32 s8, s7, 20
	s_lshl_b32 s9, s6, 9
	s_add_i32 s8, s8, s9
	s_add_u32 s8, s90, s8
	s_addc_u32 s9, s91, 0
	s_mov_b64 s[10:11], s[8:9]
	s_mov_b32 s6, s42
	s_mov_b32 s7, s44
	global_load_dword v188, v155, s[50:51]
	global_load_dwordx4 v[190:193], v154, s[8:9]
	global_load_dwordx4 v[194:197], v154, s[8:9] offset:256
	s_add_u32 s50, s50, 512
	s_addc_u32 s51, s51, 0
	s_add_u32 s8, s8, 0x10000
	s_addc_u32 s9, s9, 0
	global_load_dword v198, v155, s[50:51]
	global_load_dwordx4 v[200:203], v154, s[8:9]
	global_load_dwordx4 v[204:207], v154, s[8:9] offset:256
	s_add_u32 s50, s50, 512
	s_addc_u32 s51, s51, 0
	s_add_u32 s8, s8, 0x10000
	s_addc_u32 s9, s9, 0
	s_waitcnt vmcnt(3)
	v_mul_f32_e32 v208, 0xbfb8aa3b, v126
	v_mul_f32_e32 v209, 0xbfb8aa3b, v127
	v_mul_f32_e32 v210, 0xbfb8aa3b, v128
	v_mul_f32_e32 v211, 0xbfb8aa3b, v129
	v_exp_f32_e32 v208, v208
	v_exp_f32_e32 v209, v209
	v_exp_f32_e32 v210, v210
	v_exp_f32_e32 v211, v211
	v_add_f32_e32 v208, 1.0, v208
	v_add_f32_e32 v209, 1.0, v209
	v_add_f32_e32 v210, 1.0, v210
	v_add_f32_e32 v211, 1.0, v211
	v_rcp_f32_e32 v208, v208
	v_rcp_f32_e32 v209, v209
	v_rcp_f32_e32 v210, v210
	v_rcp_f32_e32 v211, v211
	v_pk_mul_f32 v[126:127], v[126:127], v[208:209]
	v_pk_mul_f32 v[128:129], v[128:129], v[210:211]
	v_pk_mul_f32 v[126:127], v[126:127], v[228:229]
	v_pk_mul_f32 v[128:129], v[128:129], v[230:231]
	v_pk_mul_f32 v[126:127], v[188:189], v[126:127] op_sel_hi:[0,1]
	v_pk_mul_f32 v[128:129], v[188:189], v[128:129] op_sel_hi:[0,1]
	v_mul_f32_e32 v208, 0xbfb8aa3b, v122
	v_mul_f32_e32 v209, 0xbfb8aa3b, v123
	v_mul_f32_e32 v210, 0xbfb8aa3b, v124
	v_mul_f32_e32 v211, 0xbfb8aa3b, v125
	v_exp_f32_e32 v208, v208
	v_exp_f32_e32 v209, v209
	v_exp_f32_e32 v210, v210
	v_exp_f32_e32 v211, v211
	v_add_f32_e32 v208, 1.0, v208
	v_add_f32_e32 v209, 1.0, v209
	v_add_f32_e32 v210, 1.0, v210
	v_add_f32_e32 v211, 1.0, v211
	v_rcp_f32_e32 v208, v208
	v_rcp_f32_e32 v209, v209
	v_rcp_f32_e32 v210, v210
	v_rcp_f32_e32 v211, v211
	v_pk_mul_f32 v[122:123], v[122:123], v[208:209]
	v_pk_mul_f32 v[124:125], v[124:125], v[210:211]
;   __device__ __forceinline__ void operator()(const f32x4 (&acc)[2][2][4][2], const pg8::Unit& u, int wr, int wc, int fr, int fq) const {
; #pragma unroll
;     for (int ai = 0; ai < 2; ++ai)
; #pragma unroll
;       for (int m = 0; m < 4; ++m) { const int row = u.pm * 256 + ai * 128 + wr * 64 + m * 16 + fr;
; #pragma unroll
;         for (int bj = 0; bj < 2; ++bj)
; #pragma unroll
;           for (int n = 0; n < 2; ++n) f(row, u.pn * 256 + bj * 128 + wc * 32 + n * 16 + 4 * fq, acc[ai][bj][m][n]); }
;   }
	v_pk_mul_f32 v[122:123], v[122:123], v[232:233]
	v_pk_mul_f32 v[124:125], v[124:125], v[234:235]
	v_pk_mul_f32 v[122:123], v[188:189], v[122:123] op_sel_hi:[0,1]
	v_pk_mul_f32 v[124:125], v[188:189], v[124:125] op_sel_hi:[0,1]
	v_mul_f32_e32 v208, 0xbfb8aa3b, v118
	v_mul_f32_e32 v209, 0xbfb8aa3b, v119
	v_mul_f32_e32 v210, 0xbfb8aa3b, v120
	v_mul_f32_e32 v211, 0xbfb8aa3b, v121
	v_exp_f32_e32 v208, v208
	v_exp_f32_e32 v209, v209
	v_exp_f32_e32 v210, v210
	v_exp_f32_e32 v211, v211
	v_add_f32_e32 v208, 1.0, v208
	v_add_f32_e32 v209, 1.0, v209
	v_add_f32_e32 v210, 1.0, v210
	v_add_f32_e32 v211, 1.0, v211
	v_rcp_f32_e32 v208, v208
	v_rcp_f32_e32 v209, v209
	v_rcp_f32_e32 v210, v210
	v_rcp_f32_e32 v211, v211
	v_pk_mul_f32 v[118:119], v[118:119], v[208:209]
	v_pk_mul_f32 v[120:121], v[120:121], v[210:211]
	v_pk_mul_f32 v[118:119], v[118:119], v[236:237]
	v_pk_mul_f32 v[120:121], v[120:121], v[238:239]
	v_pk_mul_f32 v[118:119], v[188:189], v[118:119] op_sel_hi:[0,1]
	v_pk_mul_f32 v[120:121], v[188:189], v[120:121] op_sel_hi:[0,1]
	v_mul_f32_e32 v208, 0xbfb8aa3b, v114
	v_mul_f32_e32 v209, 0xbfb8aa3b, v115
	v_mul_f32_e32 v210, 0xbfb8aa3b, v116
	v_mul_f32_e32 v211, 0xbfb8aa3b, v117
	v_exp_f32_e32 v208, v208
	v_exp_f32_e32 v209, v209
	v_exp_f32_e32 v210, v210
	v_exp_f32_e32 v211, v211
	v_add_f32_e32 v208, 1.0, v208
	v_add_f32_e32 v209, 1.0, v209
	v_add_f32_e32 v210, 1.0, v210
	v_add_f32_e32 v211, 1.0, v211
	v_rcp_f32_e32 v208, v208
	v_rcp_f32_e32 v209, v209
	v_rcp_f32_e32 v210, v210
	v_rcp_f32_e32 v211, v211
	v_pk_mul_f32 v[114:115], v[114:115], v[208:209]
	v_pk_mul_f32 v[116:117], v[116:117], v[210:211]
	v_pk_mul_f32 v[114:115], v[114:115], v[240:241]
	v_pk_mul_f32 v[116:117], v[116:117], v[242:243]
	v_pk_mul_f32 v[114:115], v[188:189], v[114:115] op_sel_hi:[0,1]
	v_pk_mul_f32 v[116:117], v[188:189], v[116:117] op_sel_hi:[0,1]
	v_permlane16_swap_b32_e32 v126, v122
	v_permlane16_swap_b32_e32 v127, v123
	v_permlane16_swap_b32_e32 v128, v124
	v_permlane16_swap_b32_e32 v129, v125
	v_lshlrev_b32_e32 v208, 16, v190
	v_and_b32_e32 v209, 0xffff0000, v190
	v_lshlrev_b32_e32 v210, 16, v191
	v_and_b32_e32 v211, 0xffff0000, v191
	v_lshlrev_b32_e32 v212, 16, v192
	v_and_b32_e32 v213, 0xffff0000, v192
	v_lshlrev_b32_e32 v214, 16, v193
	v_and_b32_e32 v215, 0xffff0000, v193
	v_pk_mul_f32 v[208:209], v[208:209], v[126:127]
	v_pk_mul_f32 v[210:211], v[210:211], v[128:129]
	v_pk_mul_f32 v[212:213], v[212:213], v[122:123]
	v_pk_mul_f32 v[214:215], v[214:215], v[124:125]
	v_cvt_pk_bf16_f32 v190, v208, v209
	v_cvt_pk_bf16_f32 v191, v210, v211
	v_cvt_pk_bf16_f32 v192, v212, v213
	v_cvt_pk_bf16_f32 v193, v214, v215
	v_permlane16_swap_b32_e32 v118, v114
	v_permlane16_swap_b32_e32 v119, v115
	v_permlane16_swap_b32_e32 v120, v116
	v_permlane16_swap_b32_e32 v121, v117
	v_lshlrev_b32_e32 v208, 16, v194
	v_and_b32_e32 v209, 0xffff0000, v194
	v_lshlrev_b32_e32 v210, 16, v195
	v_and_b32_e32 v211, 0xffff0000, v195
	v_lshlrev_b32_e32 v212, 16, v196
	v_and_b32_e32 v213, 0xffff0000, v196
	v_lshlrev_b32_e32 v214, 16, v197
	v_and_b32_e32 v215, 0xffff0000, v197
	v_pk_mul_f32 v[208:209], v[208:209], v[118:119]
	v_pk_mul_f32 v[210:211], v[210:211], v[120:121]
	v_pk_mul_f32 v[212:213], v[212:213], v[114:115]
	v_pk_mul_f32 v[214:215], v[214:215], v[116:117]
	v_cvt_pk_bf16_f32 v194, v208, v209
	v_cvt_pk_bf16_f32 v195, v210, v211
	v_cvt_pk_bf16_f32 v196, v212, v213
	v_cvt_pk_bf16_f32 v197, v214, v215
	global_store_dwordx4 v154, v[190:193], s[10:11]
	global_store_dwordx4 v154, v[194:197], s[10:11] offset:256
	s_add_u32 s10, s10, 0x10000
	s_addc_u32 s11, s11, 0
	global_load_dword v118, v155, s[50:51]
	global_load_dwordx4 v[126:129], v154, s[8:9]
	global_load_dwordx4 v[122:125], v154, s[8:9] offset:256
	s_add_u32 s50, s50, 512
	s_addc_u32 s51, s51, 0
	s_add_u32 s8, s8, 0x10000
	s_addc_u32 s9, s9, 0
	s_waitcnt vmcnt(5)
	v_mul_f32_e32 v208, 0xbfb8aa3b, v110
	v_mul_f32_e32 v209, 0xbfb8aa3b, v111
	v_mul_f32_e32 v210, 0xbfb8aa3b, v112
	v_mul_f32_e32 v211, 0xbfb8aa3b, v113
	v_exp_f32_e32 v208, v208
	v_exp_f32_e32 v209, v209
	v_exp_f32_e32 v210, v210
	v_exp_f32_e32 v211, v211
	v_add_f32_e32 v208, 1.0, v208
	v_add_f32_e32 v209, 1.0, v209
	v_add_f32_e32 v210, 1.0, v210
	v_add_f32_e32 v211, 1.0, v211
	v_rcp_f32_e32 v208, v208
	v_rcp_f32_e32 v209, v209
	v_rcp_f32_e32 v210, v210
	v_rcp_f32_e32 v211, v211
	v_pk_mul_f32 v[110:111], v[110:111], v[208:209]
	v_pk_mul_f32 v[112:113], v[112:113], v[210:211]
	v_pk_mul_f32 v[110:111], v[110:111], v[228:229]
	v_pk_mul_f32 v[112:113], v[112:113], v[230:231]
	v_pk_mul_f32 v[110:111], v[198:199], v[110:111] op_sel_hi:[0,1]
	v_pk_mul_f32 v[112:113], v[198:199], v[112:113] op_sel_hi:[0,1]
	v_mul_f32_e32 v208, 0xbfb8aa3b, v106
	v_mul_f32_e32 v209, 0xbfb8aa3b, v107
	v_mul_f32_e32 v210, 0xbfb8aa3b, v108
	v_mul_f32_e32 v211, 0xbfb8aa3b, v109
	v_exp_f32_e32 v208, v208
	v_exp_f32_e32 v209, v209
	v_exp_f32_e32 v210, v210
	v_exp_f32_e32 v211, v211
	v_add_f32_e32 v208, 1.0, v208
	v_add_f32_e32 v209, 1.0, v209
	v_add_f32_e32 v210, 1.0, v210
	v_add_f32_e32 v211, 1.0, v211
	v_rcp_f32_e32 v208, v208
	v_rcp_f32_e32 v209, v209
	v_rcp_f32_e32 v210, v210
	v_rcp_f32_e32 v211, v211
	v_pk_mul_f32 v[106:107], v[106:107], v[208:209]
	v_pk_mul_f32 v[108:109], v[108:109], v[210:211]
	v_pk_mul_f32 v[106:107], v[106:107], v[232:233]
	v_pk_mul_f32 v[108:109], v[108:109], v[234:235]
	v_pk_mul_f32 v[106:107], v[198:199], v[106:107] op_sel_hi:[0,1]
	v_pk_mul_f32 v[108:109], v[198:199], v[108:109] op_sel_hi:[0,1]
	v_mul_f32_e32 v208, 0xbfb8aa3b, v102
	v_mul_f32_e32 v209, 0xbfb8aa3b, v103
	v_mul_f32_e32 v210, 0xbfb8aa3b, v104
	v_mul_f32_e32 v211, 0xbfb8aa3b, v105
	v_exp_f32_e32 v208, v208
;   __device__ __forceinline__ void operator()(const f32x4 (&acc)[2][2][4][2], const pg8::Unit& u, int wr, int wc, int fr, int fq) const {
; #pragma unroll
;     for (int ai = 0; ai < 2; ++ai)
; #pragma unroll
;       for (int m = 0; m < 4; ++m) { const int row = u.pm * 256 + ai * 128 + wr * 64 + m * 16 + fr;
; #pragma unroll
;         for (int bj = 0; bj < 2; ++bj)
; #pragma unroll
;           for (int n = 0; n < 2; ++n) f(row, u.pn * 256 + bj * 128 + wc * 32 + n * 16 + 4 * fq, acc[ai][bj][m][n]); }
;   }
	v_exp_f32_e32 v209, v209
	v_exp_f32_e32 v210, v210
	v_exp_f32_e32 v211, v211
	v_add_f32_e32 v208, 1.0, v208
	v_add_f32_e32 v209, 1.0, v209
	v_add_f32_e32 v210, 1.0, v210
	v_add_f32_e32 v211, 1.0, v211
	v_rcp_f32_e32 v208, v208
	v_rcp_f32_e32 v209, v209
	v_rcp_f32_e32 v210, v210
	v_rcp_f32_e32 v211, v211
	v_pk_mul_f32 v[102:103], v[102:103], v[208:209]
	v_pk_mul_f32 v[104:105], v[104:105], v[210:211]
	v_pk_mul_f32 v[102:103], v[102:103], v[236:237]
	v_pk_mul_f32 v[104:105], v[104:105], v[238:239]
	v_pk_mul_f32 v[102:103], v[198:199], v[102:103] op_sel_hi:[0,1]
	v_pk_mul_f32 v[104:105], v[198:199], v[104:105] op_sel_hi:[0,1]
	v_mul_f32_e32 v208, 0xbfb8aa3b, v98
	v_mul_f32_e32 v209, 0xbfb8aa3b, v99
	v_mul_f32_e32 v210, 0xbfb8aa3b, v100
	v_mul_f32_e32 v211, 0xbfb8aa3b, v101
	v_exp_f32_e32 v208, v208
	v_exp_f32_e32 v209, v209
	v_exp_f32_e32 v210, v210
	v_exp_f32_e32 v211, v211
	v_add_f32_e32 v208, 1.0, v208
	v_add_f32_e32 v209, 1.0, v209
	v_add_f32_e32 v210, 1.0, v210
	v_add_f32_e32 v211, 1.0, v211
	v_rcp_f32_e32 v208, v208
	v_rcp_f32_e32 v209, v209
	v_rcp_f32_e32 v210, v210
	v_rcp_f32_e32 v211, v211
	v_pk_mul_f32 v[98:99], v[98:99], v[208:209]
	v_pk_mul_f32 v[100:101], v[100:101], v[210:211]
	v_pk_mul_f32 v[98:99], v[98:99], v[240:241]
	v_pk_mul_f32 v[100:101], v[100:101], v[242:243]
	v_pk_mul_f32 v[98:99], v[198:199], v[98:99] op_sel_hi:[0,1]
	v_pk_mul_f32 v[100:101], v[198:199], v[100:101] op_sel_hi:[0,1]
	v_permlane16_swap_b32_e32 v110, v106
	v_permlane16_swap_b32_e32 v111, v107
	v_permlane16_swap_b32_e32 v112, v108
	v_permlane16_swap_b32_e32 v113, v109
	v_lshlrev_b32_e32 v208, 16, v200
	v_and_b32_e32 v209, 0xffff0000, v200
	v_lshlrev_b32_e32 v210, 16, v201
	v_and_b32_e32 v211, 0xffff0000, v201
	v_lshlrev_b32_e32 v212, 16, v202
	v_and_b32_e32 v213, 0xffff0000, v202
	v_lshlrev_b32_e32 v214, 16, v203
	v_and_b32_e32 v215, 0xffff0000, v203
	v_pk_mul_f32 v[208:209], v[208:209], v[110:111]
	v_pk_mul_f32 v[210:211], v[210:211], v[112:113]
	v_pk_mul_f32 v[212:213], v[212:213], v[106:107]
	v_pk_mul_f32 v[214:215], v[214:215], v[108:109]
	v_cvt_pk_bf16_f32 v200, v208, v209
	v_cvt_pk_bf16_f32 v201, v210, v211
	v_cvt_pk_bf16_f32 v202, v212, v213
	v_cvt_pk_bf16_f32 v203, v214, v215
	v_permlane16_swap_b32_e32 v102, v98
	v_permlane16_swap_b32_e32 v103, v99
	v_permlane16_swap_b32_e32 v104, v100
	v_permlane16_swap_b32_e32 v105, v101
	v_lshlrev_b32_e32 v208, 16, v204
	v_and_b32_e32 v209, 0xffff0000, v204
	v_lshlrev_b32_e32 v210, 16, v205
	v_and_b32_e32 v211, 0xffff0000, v205
	v_lshlrev_b32_e32 v212, 16, v206
	v_and_b32_e32 v213, 0xffff0000, v206
	v_lshlrev_b32_e32 v214, 16, v207
	v_and_b32_e32 v215, 0xffff0000, v207
	v_pk_mul_f32 v[208:209], v[208:209], v[102:103]
	v_pk_mul_f32 v[210:211], v[210:211], v[104:105]
	v_pk_mul_f32 v[212:213], v[212:213], v[98:99]
	v_pk_mul_f32 v[214:215], v[214:215], v[100:101]
	v_cvt_pk_bf16_f32 v204, v208, v209
	v_cvt_pk_bf16_f32 v205, v210, v211
	v_cvt_pk_bf16_f32 v206, v212, v213
	v_cvt_pk_bf16_f32 v207, v214, v215
	global_store_dwordx4 v154, v[200:203], s[10:11]
	global_store_dwordx4 v154, v[204:207], s[10:11] offset:256
	s_add_u32 s10, s10, 0x10000
	s_addc_u32 s11, s11, 0
	global_load_dword v102, v155, s[50:51]
	global_load_dwordx4 v[110:113], v154, s[8:9]
	global_load_dwordx4 v[106:109], v154, s[8:9] offset:256
	s_add_u32 s50, s50, 2560
	s_addc_u32 s51, s51, 0
	s_add_u32 s8, s8, 0x50000
	s_addc_u32 s9, s9, 0
	s_waitcnt vmcnt(5)
	v_mul_f32_e32 v208, 0xbfb8aa3b, v94
	v_mul_f32_e32 v209, 0xbfb8aa3b, v95
	v_mul_f32_e32 v210, 0xbfb8aa3b, v96
	v_mul_f32_e32 v211, 0xbfb8aa3b, v97
	v_exp_f32_e32 v208, v208
	v_exp_f32_e32 v209, v209
	v_exp_f32_e32 v210, v210
	v_exp_f32_e32 v211, v211
	v_add_f32_e32 v208, 1.0, v208
	v_add_f32_e32 v209, 1.0, v209
	v_add_f32_e32 v210, 1.0, v210
	v_add_f32_e32 v211, 1.0, v211
	v_rcp_f32_e32 v208, v208
	v_rcp_f32_e32 v209, v209
	v_rcp_f32_e32 v210, v210
	v_rcp_f32_e32 v211, v211
	v_pk_mul_f32 v[94:95], v[94:95], v[208:209]
	v_pk_mul_f32 v[96:97], v[96:97], v[210:211]
	v_pk_mul_f32 v[94:95], v[94:95], v[228:229]
	v_pk_mul_f32 v[96:97], v[96:97], v[230:231]
	v_pk_mul_f32 v[94:95], v[118:119], v[94:95] op_sel_hi:[0,1]
	v_pk_mul_f32 v[96:97], v[118:119], v[96:97] op_sel_hi:[0,1]
	v_mul_f32_e32 v208, 0xbfb8aa3b, v90
	v_mul_f32_e32 v209, 0xbfb8aa3b, v91
	v_mul_f32_e32 v210, 0xbfb8aa3b, v92
	v_mul_f32_e32 v211, 0xbfb8aa3b, v93
	v_exp_f32_e32 v208, v208
	v_exp_f32_e32 v209, v209
	v_exp_f32_e32 v210, v210
	v_exp_f32_e32 v211, v211
	v_add_f32_e32 v208, 1.0, v208
	v_add_f32_e32 v209, 1.0, v209
	v_add_f32_e32 v210, 1.0, v210
	v_add_f32_e32 v211, 1.0, v211
	v_rcp_f32_e32 v208, v208
	v_rcp_f32_e32 v209, v209
	v_rcp_f32_e32 v210, v210
	v_rcp_f32_e32 v211, v211
	v_pk_mul_f32 v[90:91], v[90:91], v[208:209]
	v_pk_mul_f32 v[92:93], v[92:93], v[210:211]
	v_pk_mul_f32 v[90:91], v[90:91], v[232:233]
	v_pk_mul_f32 v[92:93], v[92:93], v[234:235]
	v_pk_mul_f32 v[90:91], v[118:119], v[90:91] op_sel_hi:[0,1]
	v_pk_mul_f32 v[92:93], v[118:119], v[92:93] op_sel_hi:[0,1]
	v_mul_f32_e32 v208, 0xbfb8aa3b, v86
	v_mul_f32_e32 v209, 0xbfb8aa3b, v87
	v_mul_f32_e32 v210, 0xbfb8aa3b, v88
	v_mul_f32_e32 v211, 0xbfb8aa3b, v89
	v_exp_f32_e32 v208, v208
	v_exp_f32_e32 v209, v209
	v_exp_f32_e32 v210, v210
	v_exp_f32_e32 v211, v211
	v_add_f32_e32 v208, 1.0, v208
	v_add_f32_e32 v209, 1.0, v209
	v_add_f32_e32 v210, 1.0, v210
	v_add_f32_e32 v211, 1.0, v211
	v_rcp_f32_e32 v208, v208
	v_rcp_f32_e32 v209, v209
	v_rcp_f32_e32 v210, v210
	v_rcp_f32_e32 v211, v211
	v_pk_mul_f32 v[86:87], v[86:87], v[208:209]
	v_pk_mul_f32 v[88:89], v[88:89], v[210:211]
	v_pk_mul_f32 v[86:87], v[86:87], v[236:237]
	v_pk_mul_f32 v[88:89], v[88:89], v[238:239]
;   __device__ __forceinline__ void operator()(const f32x4 (&acc)[2][2][4][2], const pg8::Unit& u, int wr, int wc, int fr, int fq) const {
; #pragma unroll
;     for (int ai = 0; ai < 2; ++ai)
; #pragma unroll
;       for (int m = 0; m < 4; ++m) { const int row = u.pm * 256 + ai * 128 + wr * 64 + m * 16 + fr;
; #pragma unroll
;         for (int bj = 0; bj < 2; ++bj)
; #pragma unroll
;           for (int n = 0; n < 2; ++n) f(row, u.pn * 256 + bj * 128 + wc * 32 + n * 16 + 4 * fq, acc[ai][bj][m][n]); }
;   }
	v_pk_mul_f32 v[86:87], v[118:119], v[86:87] op_sel_hi:[0,1]
	v_pk_mul_f32 v[88:89], v[118:119], v[88:89] op_sel_hi:[0,1]
	v_mul_f32_e32 v208, 0xbfb8aa3b, v82
	v_mul_f32_e32 v209, 0xbfb8aa3b, v83
	v_mul_f32_e32 v210, 0xbfb8aa3b, v84
	v_mul_f32_e32 v211, 0xbfb8aa3b, v85
	v_exp_f32_e32 v208, v208
	v_exp_f32_e32 v209, v209
	v_exp_f32_e32 v210, v210
	v_exp_f32_e32 v211, v211
	v_add_f32_e32 v208, 1.0, v208
	v_add_f32_e32 v209, 1.0, v209
	v_add_f32_e32 v210, 1.0, v210
	v_add_f32_e32 v211, 1.0, v211
	v_rcp_f32_e32 v208, v208
	v_rcp_f32_e32 v209, v209
	v_rcp_f32_e32 v210, v210
	v_rcp_f32_e32 v211, v211
	v_pk_mul_f32 v[82:83], v[82:83], v[208:209]
	v_pk_mul_f32 v[84:85], v[84:85], v[210:211]
	v_pk_mul_f32 v[82:83], v[82:83], v[240:241]
	v_pk_mul_f32 v[84:85], v[84:85], v[242:243]
	v_pk_mul_f32 v[82:83], v[118:119], v[82:83] op_sel_hi:[0,1]
	v_pk_mul_f32 v[84:85], v[118:119], v[84:85] op_sel_hi:[0,1]
	v_permlane16_swap_b32_e32 v94, v90
	v_permlane16_swap_b32_e32 v95, v91
	v_permlane16_swap_b32_e32 v96, v92
	v_permlane16_swap_b32_e32 v97, v93
	v_lshlrev_b32_e32 v208, 16, v126
	v_and_b32_e32 v209, 0xffff0000, v126
	v_lshlrev_b32_e32 v210, 16, v127
	v_and_b32_e32 v211, 0xffff0000, v127
	v_lshlrev_b32_e32 v212, 16, v128
	v_and_b32_e32 v213, 0xffff0000, v128
	v_lshlrev_b32_e32 v214, 16, v129
	v_and_b32_e32 v215, 0xffff0000, v129
	v_pk_mul_f32 v[208:209], v[208:209], v[94:95]
	v_pk_mul_f32 v[210:211], v[210:211], v[96:97]
	v_pk_mul_f32 v[212:213], v[212:213], v[90:91]
	v_pk_mul_f32 v[214:215], v[214:215], v[92:93]
	v_cvt_pk_bf16_f32 v126, v208, v209
	v_cvt_pk_bf16_f32 v127, v210, v211
	v_cvt_pk_bf16_f32 v128, v212, v213
	v_cvt_pk_bf16_f32 v129, v214, v215
	v_permlane16_swap_b32_e32 v86, v82
	v_permlane16_swap_b32_e32 v87, v83
	v_permlane16_swap_b32_e32 v88, v84
	v_permlane16_swap_b32_e32 v89, v85
	v_lshlrev_b32_e32 v208, 16, v122
	v_and_b32_e32 v209, 0xffff0000, v122
	v_lshlrev_b32_e32 v210, 16, v123
	v_and_b32_e32 v211, 0xffff0000, v123
	v_lshlrev_b32_e32 v212, 16, v124
	v_and_b32_e32 v213, 0xffff0000, v124
	v_lshlrev_b32_e32 v214, 16, v125
	v_and_b32_e32 v215, 0xffff0000, v125
	v_pk_mul_f32 v[208:209], v[208:209], v[86:87]
	v_pk_mul_f32 v[210:211], v[210:211], v[88:89]
	v_pk_mul_f32 v[212:213], v[212:213], v[82:83]
	v_pk_mul_f32 v[214:215], v[214:215], v[84:85]
	v_cvt_pk_bf16_f32 v122, v208, v209
	v_cvt_pk_bf16_f32 v123, v210, v211
	v_cvt_pk_bf16_f32 v124, v212, v213
	v_cvt_pk_bf16_f32 v125, v214, v215
	global_store_dwordx4 v154, v[126:129], s[10:11]
	global_store_dwordx4 v154, v[122:125], s[10:11] offset:256
	s_add_u32 s10, s10, 0x10000
	s_addc_u32 s11, s11, 0
	global_load_dword v86, v155, s[50:51]
	global_load_dwordx4 v[94:97], v154, s[8:9]
	global_load_dwordx4 v[90:93], v154, s[8:9] offset:256
	s_add_u32 s50, s50, 512
	s_addc_u32 s51, s51, 0
	s_add_u32 s8, s8, 0x10000
	s_addc_u32 s9, s9, 0
	s_waitcnt vmcnt(5)
	v_mul_f32_e32 v208, 0xbfb8aa3b, v78
	v_mul_f32_e32 v209, 0xbfb8aa3b, v79
	v_mul_f32_e32 v210, 0xbfb8aa3b, v80
	v_mul_f32_e32 v211, 0xbfb8aa3b, v81
	v_exp_f32_e32 v208, v208
	v_exp_f32_e32 v209, v209
	v_exp_f32_e32 v210, v210
	v_exp_f32_e32 v211, v211
	v_add_f32_e32 v208, 1.0, v208
	v_add_f32_e32 v209, 1.0, v209
	v_add_f32_e32 v210, 1.0, v210
	v_add_f32_e32 v211, 1.0, v211
	v_rcp_f32_e32 v208, v208
	v_rcp_f32_e32 v209, v209
	v_rcp_f32_e32 v210, v210
	v_rcp_f32_e32 v211, v211
	v_pk_mul_f32 v[78:79], v[78:79], v[208:209]
	v_pk_mul_f32 v[80:81], v[80:81], v[210:211]
	v_pk_mul_f32 v[78:79], v[78:79], v[228:229]
	v_pk_mul_f32 v[80:81], v[80:81], v[230:231]
	v_pk_mul_f32 v[78:79], v[102:103], v[78:79] op_sel_hi:[0,1]
	v_pk_mul_f32 v[80:81], v[102:103], v[80:81] op_sel_hi:[0,1]
	v_mul_f32_e32 v208, 0xbfb8aa3b, v74
	v_mul_f32_e32 v209, 0xbfb8aa3b, v75
	v_mul_f32_e32 v210, 0xbfb8aa3b, v76
	v_mul_f32_e32 v211, 0xbfb8aa3b, v77
	v_exp_f32_e32 v208, v208
	v_exp_f32_e32 v209, v209
	v_exp_f32_e32 v210, v210
	v_exp_f32_e32 v211, v211
	v_add_f32_e32 v208, 1.0, v208
	v_add_f32_e32 v209, 1.0, v209
	v_add_f32_e32 v210, 1.0, v210
	v_add_f32_e32 v211, 1.0, v211
	v_rcp_f32_e32 v208, v208
	v_rcp_f32_e32 v209, v209
	v_rcp_f32_e32 v210, v210
	v_rcp_f32_e32 v211, v211
	v_pk_mul_f32 v[74:75], v[74:75], v[208:209]
	v_pk_mul_f32 v[76:77], v[76:77], v[210:211]
	v_pk_mul_f32 v[74:75], v[74:75], v[232:233]
	v_pk_mul_f32 v[76:77], v[76:77], v[234:235]
	v_pk_mul_f32 v[74:75], v[102:103], v[74:75] op_sel_hi:[0,1]
	v_pk_mul_f32 v[76:77], v[102:103], v[76:77] op_sel_hi:[0,1]
	v_mul_f32_e32 v208, 0xbfb8aa3b, v70
	v_mul_f32_e32 v209, 0xbfb8aa3b, v71
	v_mul_f32_e32 v210, 0xbfb8aa3b, v72
	v_mul_f32_e32 v211, 0xbfb8aa3b, v73
	v_exp_f32_e32 v208, v208
	v_exp_f32_e32 v209, v209
	v_exp_f32_e32 v210, v210
	v_exp_f32_e32 v211, v211
	v_add_f32_e32 v208, 1.0, v208
	v_add_f32_e32 v209, 1.0, v209
	v_add_f32_e32 v210, 1.0, v210
	v_add_f32_e32 v211, 1.0, v211
	v_rcp_f32_e32 v208, v208
	v_rcp_f32_e32 v209, v209
	v_rcp_f32_e32 v210, v210
	v_rcp_f32_e32 v211, v211
	v_pk_mul_f32 v[70:71], v[70:71], v[208:209]
	v_pk_mul_f32 v[72:73], v[72:73], v[210:211]
	v_pk_mul_f32 v[70:71], v[70:71], v[236:237]
	v_pk_mul_f32 v[72:73], v[72:73], v[238:239]
	v_pk_mul_f32 v[70:71], v[102:103], v[70:71] op_sel_hi:[0,1]
	v_pk_mul_f32 v[72:73], v[102:103], v[72:73] op_sel_hi:[0,1]
	v_mul_f32_e32 v208, 0xbfb8aa3b, v66
	v_mul_f32_e32 v209, 0xbfb8aa3b, v67
	v_mul_f32_e32 v210, 0xbfb8aa3b, v68
	v_mul_f32_e32 v211, 0xbfb8aa3b, v69
	v_exp_f32_e32 v208, v208
	v_exp_f32_e32 v209, v209
	v_exp_f32_e32 v210, v210
	v_exp_f32_e32 v211, v211
	v_add_f32_e32 v208, 1.0, v208
	v_add_f32_e32 v209, 1.0, v209
	v_add_f32_e32 v210, 1.0, v210
	v_add_f32_e32 v211, 1.0, v211
	v_rcp_f32_e32 v208, v208
	v_rcp_f32_e32 v209, v209
	v_rcp_f32_e32 v210, v210
;   __device__ __forceinline__ void operator()(const f32x4 (&acc)[2][2][4][2], const pg8::Unit& u, int wr, int wc, int fr, int fq) const {
; #pragma unroll
;     for (int ai = 0; ai < 2; ++ai)
; #pragma unroll
;       for (int m = 0; m < 4; ++m) { const int row = u.pm * 256 + ai * 128 + wr * 64 + m * 16 + fr;
; #pragma unroll
;         for (int bj = 0; bj < 2; ++bj)
; #pragma unroll
;           for (int n = 0; n < 2; ++n) f(row, u.pn * 256 + bj * 128 + wc * 32 + n * 16 + 4 * fq, acc[ai][bj][m][n]); }
;   }
	v_rcp_f32_e32 v211, v211
	v_pk_mul_f32 v[66:67], v[66:67], v[208:209]
	v_pk_mul_f32 v[68:69], v[68:69], v[210:211]
	v_pk_mul_f32 v[66:67], v[66:67], v[240:241]
	v_pk_mul_f32 v[68:69], v[68:69], v[242:243]
	v_pk_mul_f32 v[66:67], v[102:103], v[66:67] op_sel_hi:[0,1]
	v_pk_mul_f32 v[68:69], v[102:103], v[68:69] op_sel_hi:[0,1]
	v_permlane16_swap_b32_e32 v78, v74
	v_permlane16_swap_b32_e32 v79, v75
	v_permlane16_swap_b32_e32 v80, v76
	v_permlane16_swap_b32_e32 v81, v77
	v_lshlrev_b32_e32 v208, 16, v110
	v_and_b32_e32 v209, 0xffff0000, v110
	v_lshlrev_b32_e32 v210, 16, v111
	v_and_b32_e32 v211, 0xffff0000, v111
	v_lshlrev_b32_e32 v212, 16, v112
	v_and_b32_e32 v213, 0xffff0000, v112
	v_lshlrev_b32_e32 v214, 16, v113
	v_and_b32_e32 v215, 0xffff0000, v113
	v_pk_mul_f32 v[208:209], v[208:209], v[78:79]
	v_pk_mul_f32 v[210:211], v[210:211], v[80:81]
	v_pk_mul_f32 v[212:213], v[212:213], v[74:75]
	v_pk_mul_f32 v[214:215], v[214:215], v[76:77]
	v_cvt_pk_bf16_f32 v110, v208, v209
	v_cvt_pk_bf16_f32 v111, v210, v211
	v_cvt_pk_bf16_f32 v112, v212, v213
	v_cvt_pk_bf16_f32 v113, v214, v215
	v_permlane16_swap_b32_e32 v70, v66
	v_permlane16_swap_b32_e32 v71, v67
	v_permlane16_swap_b32_e32 v72, v68
	v_permlane16_swap_b32_e32 v73, v69
	v_lshlrev_b32_e32 v208, 16, v106
	v_and_b32_e32 v209, 0xffff0000, v106
	v_lshlrev_b32_e32 v210, 16, v107
	v_and_b32_e32 v211, 0xffff0000, v107
	v_lshlrev_b32_e32 v212, 16, v108
	v_and_b32_e32 v213, 0xffff0000, v108
	v_lshlrev_b32_e32 v214, 16, v109
	v_and_b32_e32 v215, 0xffff0000, v109
	v_pk_mul_f32 v[208:209], v[208:209], v[70:71]
	v_pk_mul_f32 v[210:211], v[210:211], v[72:73]
	v_pk_mul_f32 v[212:213], v[212:213], v[66:67]
	v_pk_mul_f32 v[214:215], v[214:215], v[68:69]
	v_cvt_pk_bf16_f32 v106, v208, v209
	v_cvt_pk_bf16_f32 v107, v210, v211
	v_cvt_pk_bf16_f32 v108, v212, v213
	v_cvt_pk_bf16_f32 v109, v214, v215
	global_store_dwordx4 v154, v[110:113], s[10:11]
	global_store_dwordx4 v154, v[106:109], s[10:11] offset:256
	s_add_u32 s10, s10, 0x50000
	s_addc_u32 s11, s11, 0
	global_load_dword v70, v155, s[50:51]
	global_load_dwordx4 v[78:81], v154, s[8:9]
	global_load_dwordx4 v[74:77], v154, s[8:9] offset:256
	s_add_u32 s50, s50, 512
	s_addc_u32 s51, s51, 0
	s_add_u32 s8, s8, 0x10000
	s_addc_u32 s9, s9, 0
	s_waitcnt vmcnt(5)
	v_mul_f32_e32 v208, 0xbfb8aa3b, v62
	v_mul_f32_e32 v209, 0xbfb8aa3b, v63
	v_mul_f32_e32 v210, 0xbfb8aa3b, v64
	v_mul_f32_e32 v211, 0xbfb8aa3b, v65
	v_exp_f32_e32 v208, v208
	v_exp_f32_e32 v209, v209
	v_exp_f32_e32 v210, v210
	v_exp_f32_e32 v211, v211
	v_add_f32_e32 v208, 1.0, v208
	v_add_f32_e32 v209, 1.0, v209
	v_add_f32_e32 v210, 1.0, v210
	v_add_f32_e32 v211, 1.0, v211
	v_rcp_f32_e32 v208, v208
	v_rcp_f32_e32 v209, v209
	v_rcp_f32_e32 v210, v210
	v_rcp_f32_e32 v211, v211
	v_pk_mul_f32 v[62:63], v[62:63], v[208:209]
	v_pk_mul_f32 v[64:65], v[64:65], v[210:211]
	v_pk_mul_f32 v[62:63], v[62:63], v[228:229]
	v_pk_mul_f32 v[64:65], v[64:65], v[230:231]
	v_pk_mul_f32 v[62:63], v[86:87], v[62:63] op_sel_hi:[0,1]
	v_pk_mul_f32 v[64:65], v[86:87], v[64:65] op_sel_hi:[0,1]
	v_mul_f32_e32 v208, 0xbfb8aa3b, v58
	v_mul_f32_e32 v209, 0xbfb8aa3b, v59
	v_mul_f32_e32 v210, 0xbfb8aa3b, v60
	v_mul_f32_e32 v211, 0xbfb8aa3b, v61
	v_exp_f32_e32 v208, v208
	v_exp_f32_e32 v209, v209
	v_exp_f32_e32 v210, v210
	v_exp_f32_e32 v211, v211
	v_add_f32_e32 v208, 1.0, v208
	v_add_f32_e32 v209, 1.0, v209
	v_add_f32_e32 v210, 1.0, v210
	v_add_f32_e32 v211, 1.0, v211
	v_rcp_f32_e32 v208, v208
	v_rcp_f32_e32 v209, v209
	v_rcp_f32_e32 v210, v210
	v_rcp_f32_e32 v211, v211
	v_pk_mul_f32 v[58:59], v[58:59], v[208:209]
	v_pk_mul_f32 v[60:61], v[60:61], v[210:211]
	v_pk_mul_f32 v[58:59], v[58:59], v[232:233]
	v_pk_mul_f32 v[60:61], v[60:61], v[234:235]
	v_pk_mul_f32 v[58:59], v[86:87], v[58:59] op_sel_hi:[0,1]
	v_pk_mul_f32 v[60:61], v[86:87], v[60:61] op_sel_hi:[0,1]
	v_mul_f32_e32 v208, 0xbfb8aa3b, v54
	v_mul_f32_e32 v209, 0xbfb8aa3b, v55
	v_mul_f32_e32 v210, 0xbfb8aa3b, v56
	v_mul_f32_e32 v211, 0xbfb8aa3b, v57
	v_exp_f32_e32 v208, v208
	v_exp_f32_e32 v209, v209
	v_exp_f32_e32 v210, v210
	v_exp_f32_e32 v211, v211
	v_add_f32_e32 v208, 1.0, v208
	v_add_f32_e32 v209, 1.0, v209
	v_add_f32_e32 v210, 1.0, v210
	v_add_f32_e32 v211, 1.0, v211
	v_rcp_f32_e32 v208, v208
	v_rcp_f32_e32 v209, v209
	v_rcp_f32_e32 v210, v210
	v_rcp_f32_e32 v211, v211
	v_pk_mul_f32 v[54:55], v[54:55], v[208:209]
	v_pk_mul_f32 v[56:57], v[56:57], v[210:211]
	v_pk_mul_f32 v[54:55], v[54:55], v[236:237]
	v_pk_mul_f32 v[56:57], v[56:57], v[238:239]
	v_pk_mul_f32 v[54:55], v[86:87], v[54:55] op_sel_hi:[0,1]
	v_pk_mul_f32 v[56:57], v[86:87], v[56:57] op_sel_hi:[0,1]
	v_mul_f32_e32 v208, 0xbfb8aa3b, v50
	v_mul_f32_e32 v209, 0xbfb8aa3b, v51
	v_mul_f32_e32 v210, 0xbfb8aa3b, v52
	v_mul_f32_e32 v211, 0xbfb8aa3b, v53
	v_exp_f32_e32 v208, v208
	v_exp_f32_e32 v209, v209
	v_exp_f32_e32 v210, v210
	v_exp_f32_e32 v211, v211
	v_add_f32_e32 v208, 1.0, v208
	v_add_f32_e32 v209, 1.0, v209
	v_add_f32_e32 v210, 1.0, v210
	v_add_f32_e32 v211, 1.0, v211
	v_rcp_f32_e32 v208, v208
	v_rcp_f32_e32 v209, v209
	v_rcp_f32_e32 v210, v210
	v_rcp_f32_e32 v211, v211
	v_pk_mul_f32 v[50:51], v[50:51], v[208:209]
	v_pk_mul_f32 v[52:53], v[52:53], v[210:211]
	v_pk_mul_f32 v[50:51], v[50:51], v[240:241]
	v_pk_mul_f32 v[52:53], v[52:53], v[242:243]
	v_pk_mul_f32 v[50:51], v[86:87], v[50:51] op_sel_hi:[0,1]
	v_pk_mul_f32 v[52:53], v[86:87], v[52:53] op_sel_hi:[0,1]
	v_permlane16_swap_b32_e32 v62, v58
	v_permlane16_swap_b32_e32 v63, v59
	v_permlane16_swap_b32_e32 v64, v60
	v_permlane16_swap_b32_e32 v65, v61
	v_lshlrev_b32_e32 v208, 16, v94
	v_and_b32_e32 v209, 0xffff0000, v94
	v_lshlrev_b32_e32 v210, 16, v95
;   __device__ __forceinline__ void operator()(const f32x4 (&acc)[2][2][4][2], const pg8::Unit& u, int wr, int wc, int fr, int fq) const {
; #pragma unroll
;     for (int ai = 0; ai < 2; ++ai)
; #pragma unroll
;       for (int m = 0; m < 4; ++m) { const int row = u.pm * 256 + ai * 128 + wr * 64 + m * 16 + fr;
; #pragma unroll
;         for (int bj = 0; bj < 2; ++bj)
; #pragma unroll
;           for (int n = 0; n < 2; ++n) f(row, u.pn * 256 + bj * 128 + wc * 32 + n * 16 + 4 * fq, acc[ai][bj][m][n]); }
;   }
	v_and_b32_e32 v211, 0xffff0000, v95
	v_lshlrev_b32_e32 v212, 16, v96
	v_and_b32_e32 v213, 0xffff0000, v96
	v_lshlrev_b32_e32 v214, 16, v97
	v_and_b32_e32 v215, 0xffff0000, v97
	v_pk_mul_f32 v[208:209], v[208:209], v[62:63]
	v_pk_mul_f32 v[210:211], v[210:211], v[64:65]
	v_pk_mul_f32 v[212:213], v[212:213], v[58:59]
	v_pk_mul_f32 v[214:215], v[214:215], v[60:61]
	v_cvt_pk_bf16_f32 v94, v208, v209
	v_cvt_pk_bf16_f32 v95, v210, v211
	v_cvt_pk_bf16_f32 v96, v212, v213
	v_cvt_pk_bf16_f32 v97, v214, v215
	v_permlane16_swap_b32_e32 v54, v50
	v_permlane16_swap_b32_e32 v55, v51
	v_permlane16_swap_b32_e32 v56, v52
	v_permlane16_swap_b32_e32 v57, v53
	v_lshlrev_b32_e32 v208, 16, v90
	v_and_b32_e32 v209, 0xffff0000, v90
	v_lshlrev_b32_e32 v210, 16, v91
	v_and_b32_e32 v211, 0xffff0000, v91
	v_lshlrev_b32_e32 v212, 16, v92
	v_and_b32_e32 v213, 0xffff0000, v92
	v_lshlrev_b32_e32 v214, 16, v93
	v_and_b32_e32 v215, 0xffff0000, v93
	v_pk_mul_f32 v[208:209], v[208:209], v[54:55]
	v_pk_mul_f32 v[210:211], v[210:211], v[56:57]
	v_pk_mul_f32 v[212:213], v[212:213], v[50:51]
	v_pk_mul_f32 v[214:215], v[214:215], v[52:53]
	v_cvt_pk_bf16_f32 v90, v208, v209
	v_cvt_pk_bf16_f32 v91, v210, v211
	v_cvt_pk_bf16_f32 v92, v212, v213
	v_cvt_pk_bf16_f32 v93, v214, v215
	global_store_dwordx4 v154, v[94:97], s[10:11]
	global_store_dwordx4 v154, v[90:93], s[10:11] offset:256
	s_add_u32 s10, s10, 0x10000
	s_addc_u32 s11, s11, 0
	global_load_dword v54, v155, s[50:51]
	global_load_dwordx4 v[62:65], v154, s[8:9]
	global_load_dwordx4 v[58:61], v154, s[8:9] offset:256
	s_add_u32 s50, s50, 512
	s_addc_u32 s51, s51, 0
	s_add_u32 s8, s8, 0x10000
	s_addc_u32 s9, s9, 0
	s_waitcnt vmcnt(5)
	v_mul_f32_e32 v208, 0xbfb8aa3b, v46
	v_mul_f32_e32 v209, 0xbfb8aa3b, v47
	v_mul_f32_e32 v210, 0xbfb8aa3b, v48
	v_mul_f32_e32 v211, 0xbfb8aa3b, v49
	v_exp_f32_e32 v208, v208
	v_exp_f32_e32 v209, v209
	v_exp_f32_e32 v210, v210
	v_exp_f32_e32 v211, v211
	v_add_f32_e32 v208, 1.0, v208
	v_add_f32_e32 v209, 1.0, v209
	v_add_f32_e32 v210, 1.0, v210
	v_add_f32_e32 v211, 1.0, v211
	v_rcp_f32_e32 v208, v208
	v_rcp_f32_e32 v209, v209
	v_rcp_f32_e32 v210, v210
	v_rcp_f32_e32 v211, v211
	v_pk_mul_f32 v[46:47], v[46:47], v[208:209]
	v_pk_mul_f32 v[48:49], v[48:49], v[210:211]
	v_pk_mul_f32 v[46:47], v[46:47], v[228:229]
	v_pk_mul_f32 v[48:49], v[48:49], v[230:231]
	v_pk_mul_f32 v[46:47], v[70:71], v[46:47] op_sel_hi:[0,1]
	v_pk_mul_f32 v[48:49], v[70:71], v[48:49] op_sel_hi:[0,1]
	v_mul_f32_e32 v208, 0xbfb8aa3b, v42
	v_mul_f32_e32 v209, 0xbfb8aa3b, v43
	v_mul_f32_e32 v210, 0xbfb8aa3b, v44
	v_mul_f32_e32 v211, 0xbfb8aa3b, v45
	v_exp_f32_e32 v208, v208
	v_exp_f32_e32 v209, v209
	v_exp_f32_e32 v210, v210
	v_exp_f32_e32 v211, v211
	v_add_f32_e32 v208, 1.0, v208
	v_add_f32_e32 v209, 1.0, v209
	v_add_f32_e32 v210, 1.0, v210
	v_add_f32_e32 v211, 1.0, v211
	v_rcp_f32_e32 v208, v208
	v_rcp_f32_e32 v209, v209
	v_rcp_f32_e32 v210, v210
	v_rcp_f32_e32 v211, v211
	v_pk_mul_f32 v[42:43], v[42:43], v[208:209]
	v_pk_mul_f32 v[44:45], v[44:45], v[210:211]
	v_pk_mul_f32 v[42:43], v[42:43], v[232:233]
	v_pk_mul_f32 v[44:45], v[44:45], v[234:235]
	v_pk_mul_f32 v[42:43], v[70:71], v[42:43] op_sel_hi:[0,1]
	v_pk_mul_f32 v[44:45], v[70:71], v[44:45] op_sel_hi:[0,1]
	v_mul_f32_e32 v208, 0xbfb8aa3b, v38
	v_mul_f32_e32 v209, 0xbfb8aa3b, v39
	v_mul_f32_e32 v210, 0xbfb8aa3b, v40
	v_mul_f32_e32 v211, 0xbfb8aa3b, v41
	v_exp_f32_e32 v208, v208
	v_exp_f32_e32 v209, v209
	v_exp_f32_e32 v210, v210
	v_exp_f32_e32 v211, v211
	v_add_f32_e32 v208, 1.0, v208
	v_add_f32_e32 v209, 1.0, v209
	v_add_f32_e32 v210, 1.0, v210
	v_add_f32_e32 v211, 1.0, v211
	v_rcp_f32_e32 v208, v208
	v_rcp_f32_e32 v209, v209
	v_rcp_f32_e32 v210, v210
	v_rcp_f32_e32 v211, v211
	v_pk_mul_f32 v[38:39], v[38:39], v[208:209]
	v_pk_mul_f32 v[40:41], v[40:41], v[210:211]
	v_pk_mul_f32 v[38:39], v[38:39], v[236:237]
	v_pk_mul_f32 v[40:41], v[40:41], v[238:239]
	v_pk_mul_f32 v[38:39], v[70:71], v[38:39] op_sel_hi:[0,1]
	v_pk_mul_f32 v[40:41], v[70:71], v[40:41] op_sel_hi:[0,1]
	v_mul_f32_e32 v208, 0xbfb8aa3b, v34
	v_mul_f32_e32 v209, 0xbfb8aa3b, v35
	v_mul_f32_e32 v210, 0xbfb8aa3b, v36
	v_mul_f32_e32 v211, 0xbfb8aa3b, v37
	v_exp_f32_e32 v208, v208
	v_exp_f32_e32 v209, v209
	v_exp_f32_e32 v210, v210
	v_exp_f32_e32 v211, v211
	v_add_f32_e32 v208, 1.0, v208
	v_add_f32_e32 v209, 1.0, v209
	v_add_f32_e32 v210, 1.0, v210
	v_add_f32_e32 v211, 1.0, v211
	v_rcp_f32_e32 v208, v208
	v_rcp_f32_e32 v209, v209
	v_rcp_f32_e32 v210, v210
	v_rcp_f32_e32 v211, v211
	v_pk_mul_f32 v[34:35], v[34:35], v[208:209]
	v_pk_mul_f32 v[36:37], v[36:37], v[210:211]
	v_pk_mul_f32 v[34:35], v[34:35], v[240:241]
	v_pk_mul_f32 v[36:37], v[36:37], v[242:243]
	v_pk_mul_f32 v[34:35], v[70:71], v[34:35] op_sel_hi:[0,1]
	v_pk_mul_f32 v[36:37], v[70:71], v[36:37] op_sel_hi:[0,1]
	v_permlane16_swap_b32_e32 v46, v42
	v_permlane16_swap_b32_e32 v47, v43
	v_permlane16_swap_b32_e32 v48, v44
	v_permlane16_swap_b32_e32 v49, v45
	v_lshlrev_b32_e32 v208, 16, v78
	v_and_b32_e32 v209, 0xffff0000, v78
	v_lshlrev_b32_e32 v210, 16, v79
	v_and_b32_e32 v211, 0xffff0000, v79
	v_lshlrev_b32_e32 v212, 16, v80
	v_and_b32_e32 v213, 0xffff0000, v80
	v_lshlrev_b32_e32 v214, 16, v81
	v_and_b32_e32 v215, 0xffff0000, v81
	v_pk_mul_f32 v[208:209], v[208:209], v[46:47]
	v_pk_mul_f32 v[210:211], v[210:211], v[48:49]
	v_pk_mul_f32 v[212:213], v[212:213], v[42:43]
	v_pk_mul_f32 v[214:215], v[214:215], v[44:45]
	v_cvt_pk_bf16_f32 v78, v208, v209
	v_cvt_pk_bf16_f32 v79, v210, v211
	v_cvt_pk_bf16_f32 v80, v212, v213
	v_cvt_pk_bf16_f32 v81, v214, v215
	v_permlane16_swap_b32_e32 v38, v34
	v_permlane16_swap_b32_e32 v39, v35
	v_permlane16_swap_b32_e32 v40, v36
	v_permlane16_swap_b32_e32 v41, v37
	v_lshlrev_b32_e32 v208, 16, v74
	v_and_b32_e32 v209, 0xffff0000, v74
	v_lshlrev_b32_e32 v210, 16, v75
	v_and_b32_e32 v211, 0xffff0000, v75
	v_lshlrev_b32_e32 v212, 16, v76
	v_and_b32_e32 v213, 0xffff0000, v76
	v_lshlrev_b32_e32 v214, 16, v77
	v_and_b32_e32 v215, 0xffff0000, v77
	v_pk_mul_f32 v[208:209], v[208:209], v[38:39]
	v_pk_mul_f32 v[210:211], v[210:211], v[40:41]
	v_pk_mul_f32 v[212:213], v[212:213], v[34:35]
	v_pk_mul_f32 v[214:215], v[214:215], v[36:37]
	v_cvt_pk_bf16_f32 v74, v208, v209
	v_cvt_pk_bf16_f32 v75, v210, v211
	v_cvt_pk_bf16_f32 v76, v212, v213
	v_cvt_pk_bf16_f32 v77, v214, v215
	global_store_dwordx4 v154, v[78:81], s[10:11]
	global_store_dwordx4 v154, v[74:77], s[10:11] offset:256
	s_add_u32 s10, s10, 0x10000
	s_addc_u32 s11, s11, 0
	global_load_dword v38, v155, s[50:51]
	global_load_dwordx4 v[46:49], v154, s[8:9]
	global_load_dwordx4 v[42:45], v154, s[8:9] offset:256
	s_waitcnt vmcnt(5)
;   __device__ __forceinline__ void operator()(const f32x4 (&acc)[2][2][4][2], const pg8::Unit& u, int wr, int wc, int fr, int fq) const {
;     ...
;       for (int m = 0; m < 4; ++m) { const int row = u.pm * 256 + ai * 128 + wr * 64 + m * 16 + fr;
; #pragma unroll
;         for (int bj = 0; bj < 2; ++bj)
; #pragma unroll
;           for (int n = 0; n < 2; ++n) f(row, u.pn * 256 + bj * 128 + wc * 32 + n * 16 + 4 * fq, acc[ai][bj][m][n]); }
	v_mul_f32_e32 v208, 0xbfb8aa3b, v30
	v_mul_f32_e32 v209, 0xbfb8aa3b, v31
	v_mul_f32_e32 v210, 0xbfb8aa3b, v32
	v_mul_f32_e32 v211, 0xbfb8aa3b, v33
	v_exp_f32_e32 v208, v208
	v_exp_f32_e32 v209, v209
	v_exp_f32_e32 v210, v210
	v_exp_f32_e32 v211, v211
	v_add_f32_e32 v208, 1.0, v208
	v_add_f32_e32 v209, 1.0, v209
	v_add_f32_e32 v210, 1.0, v210
	v_add_f32_e32 v211, 1.0, v211
	v_rcp_f32_e32 v208, v208
	v_rcp_f32_e32 v209, v209
	v_rcp_f32_e32 v210, v210
	v_rcp_f32_e32 v211, v211
	v_pk_mul_f32 v[30:31], v[30:31], v[208:209]
	v_pk_mul_f32 v[32:33], v[32:33], v[210:211]
	v_pk_mul_f32 v[30:31], v[30:31], v[228:229]
	v_pk_mul_f32 v[32:33], v[32:33], v[230:231]
	v_pk_mul_f32 v[30:31], v[54:55], v[30:31] op_sel_hi:[0,1]
	v_pk_mul_f32 v[32:33], v[54:55], v[32:33] op_sel_hi:[0,1]
	v_mul_f32_e32 v208, 0xbfb8aa3b, v26
	v_mul_f32_e32 v209, 0xbfb8aa3b, v27
	v_mul_f32_e32 v210, 0xbfb8aa3b, v28
	v_mul_f32_e32 v211, 0xbfb8aa3b, v29
	v_exp_f32_e32 v208, v208
	v_exp_f32_e32 v209, v209
	v_exp_f32_e32 v210, v210
	v_exp_f32_e32 v211, v211
	v_add_f32_e32 v208, 1.0, v208
	v_add_f32_e32 v209, 1.0, v209
	v_add_f32_e32 v210, 1.0, v210
	v_add_f32_e32 v211, 1.0, v211
	v_rcp_f32_e32 v208, v208
	v_rcp_f32_e32 v209, v209
	v_rcp_f32_e32 v210, v210
	v_rcp_f32_e32 v211, v211
	v_pk_mul_f32 v[26:27], v[26:27], v[208:209]
	v_pk_mul_f32 v[28:29], v[28:29], v[210:211]
	v_pk_mul_f32 v[26:27], v[26:27], v[232:233]
	v_pk_mul_f32 v[28:29], v[28:29], v[234:235]
	v_pk_mul_f32 v[26:27], v[54:55], v[26:27] op_sel_hi:[0,1]
	v_pk_mul_f32 v[28:29], v[54:55], v[28:29] op_sel_hi:[0,1]
	v_mul_f32_e32 v208, 0xbfb8aa3b, v22
	v_mul_f32_e32 v209, 0xbfb8aa3b, v23
	v_mul_f32_e32 v210, 0xbfb8aa3b, v24
	v_mul_f32_e32 v211, 0xbfb8aa3b, v25
	v_exp_f32_e32 v208, v208
	v_exp_f32_e32 v209, v209
	v_exp_f32_e32 v210, v210
	v_exp_f32_e32 v211, v211
	v_add_f32_e32 v208, 1.0, v208
	v_add_f32_e32 v209, 1.0, v209
	v_add_f32_e32 v210, 1.0, v210
	v_add_f32_e32 v211, 1.0, v211
	v_rcp_f32_e32 v208, v208
	v_rcp_f32_e32 v209, v209
	v_rcp_f32_e32 v210, v210
	v_rcp_f32_e32 v211, v211
	v_pk_mul_f32 v[22:23], v[22:23], v[208:209]
	v_pk_mul_f32 v[24:25], v[24:25], v[210:211]
	v_pk_mul_f32 v[22:23], v[22:23], v[236:237]
	v_pk_mul_f32 v[24:25], v[24:25], v[238:239]
	v_pk_mul_f32 v[22:23], v[54:55], v[22:23] op_sel_hi:[0,1]
	v_pk_mul_f32 v[24:25], v[54:55], v[24:25] op_sel_hi:[0,1]
	v_mul_f32_e32 v208, 0xbfb8aa3b, v18
	v_mul_f32_e32 v209, 0xbfb8aa3b, v19
	v_mul_f32_e32 v210, 0xbfb8aa3b, v20
	v_mul_f32_e32 v211, 0xbfb8aa3b, v21
	v_exp_f32_e32 v208, v208
	v_exp_f32_e32 v209, v209
	v_exp_f32_e32 v210, v210
	v_exp_f32_e32 v211, v211
	v_add_f32_e32 v208, 1.0, v208
	v_add_f32_e32 v209, 1.0, v209
	v_add_f32_e32 v210, 1.0, v210
	v_add_f32_e32 v211, 1.0, v211
	v_rcp_f32_e32 v208, v208
	v_rcp_f32_e32 v209, v209
	v_rcp_f32_e32 v210, v210
	v_rcp_f32_e32 v211, v211
	v_pk_mul_f32 v[18:19], v[18:19], v[208:209]
	v_pk_mul_f32 v[20:21], v[20:21], v[210:211]
	v_pk_mul_f32 v[18:19], v[18:19], v[240:241]
	v_pk_mul_f32 v[20:21], v[20:21], v[242:243]
	v_pk_mul_f32 v[18:19], v[54:55], v[18:19] op_sel_hi:[0,1]
	v_pk_mul_f32 v[20:21], v[54:55], v[20:21] op_sel_hi:[0,1]
	v_permlane16_swap_b32_e32 v30, v26
	v_permlane16_swap_b32_e32 v31, v27
	v_permlane16_swap_b32_e32 v32, v28
	v_permlane16_swap_b32_e32 v33, v29
	v_lshlrev_b32_e32 v208, 16, v62
	v_and_b32_e32 v209, 0xffff0000, v62
	v_lshlrev_b32_e32 v210, 16, v63
	v_and_b32_e32 v211, 0xffff0000, v63
	v_lshlrev_b32_e32 v212, 16, v64
	v_and_b32_e32 v213, 0xffff0000, v64
	v_lshlrev_b32_e32 v214, 16, v65
	v_and_b32_e32 v215, 0xffff0000, v65
	v_pk_mul_f32 v[208:209], v[208:209], v[30:31]
	v_pk_mul_f32 v[210:211], v[210:211], v[32:33]
	v_pk_mul_f32 v[212:213], v[212:213], v[26:27]
	v_pk_mul_f32 v[214:215], v[214:215], v[28:29]
	v_cvt_pk_bf16_f32 v62, v208, v209
	v_cvt_pk_bf16_f32 v63, v210, v211
	v_cvt_pk_bf16_f32 v64, v212, v213
	v_cvt_pk_bf16_f32 v65, v214, v215
	v_permlane16_swap_b32_e32 v22, v18
	v_permlane16_swap_b32_e32 v23, v19
	v_permlane16_swap_b32_e32 v24, v20
	v_permlane16_swap_b32_e32 v25, v21
	v_lshlrev_b32_e32 v208, 16, v58
	v_and_b32_e32 v209, 0xffff0000, v58
	v_lshlrev_b32_e32 v210, 16, v59
	v_and_b32_e32 v211, 0xffff0000, v59
	v_lshlrev_b32_e32 v212, 16, v60
	v_and_b32_e32 v213, 0xffff0000, v60
	v_lshlrev_b32_e32 v214, 16, v61
	v_and_b32_e32 v215, 0xffff0000, v61
	v_pk_mul_f32 v[208:209], v[208:209], v[22:23]
	v_pk_mul_f32 v[210:211], v[210:211], v[24:25]
	v_pk_mul_f32 v[212:213], v[212:213], v[18:19]
	v_pk_mul_f32 v[214:215], v[214:215], v[20:21]
	v_cvt_pk_bf16_f32 v58, v208, v209
	v_cvt_pk_bf16_f32 v59, v210, v211
	v_cvt_pk_bf16_f32 v60, v212, v213
	v_cvt_pk_bf16_f32 v61, v214, v215
	global_store_dwordx4 v154, v[62:65], s[10:11]
	global_store_dwordx4 v154, v[58:61], s[10:11] offset:256
	s_add_u32 s10, s10, 0x10000
	s_addc_u32 s11, s11, 0
	s_waitcnt vmcnt(2)
;   __device__ __forceinline__ void operator()(const f32x4 (&acc)[2][2][4][2], const pg8::Unit& u, int wr, int wc, int fr, int fq) const {
;     ...
;       for (int m = 0; m < 4; ++m) { const int row = u.pm * 256 + ai * 128 + wr * 64 + m * 16 + fr;
; #pragma unroll
;         for (int bj = 0; bj < 2; ++bj)
; #pragma unroll
;           for (int n = 0; n < 2; ++n) f(row, u.pn * 256 + bj * 128 + wc * 32 + n * 16 + 4 * fq, acc[ai][bj][m][n]); }
	v_mul_f32_e32 v208, 0xbfb8aa3b, v14
	v_mul_f32_e32 v209, 0xbfb8aa3b, v15
	v_mul_f32_e32 v210, 0xbfb8aa3b, v16
	v_mul_f32_e32 v211, 0xbfb8aa3b, v17
	v_exp_f32_e32 v208, v208
	v_exp_f32_e32 v209, v209
	v_exp_f32_e32 v210, v210
	v_exp_f32_e32 v211, v211
	v_add_f32_e32 v208, 1.0, v208
	v_add_f32_e32 v209, 1.0, v209
	v_add_f32_e32 v210, 1.0, v210
	v_add_f32_e32 v211, 1.0, v211
	v_rcp_f32_e32 v208, v208
	v_rcp_f32_e32 v209, v209
	v_rcp_f32_e32 v210, v210
	v_rcp_f32_e32 v211, v211
	v_pk_mul_f32 v[14:15], v[14:15], v[208:209]
	v_pk_mul_f32 v[16:17], v[16:17], v[210:211]
	v_pk_mul_f32 v[14:15], v[14:15], v[228:229]
	v_pk_mul_f32 v[16:17], v[16:17], v[230:231]
	v_pk_mul_f32 v[14:15], v[38:39], v[14:15] op_sel_hi:[0,1]
	v_pk_mul_f32 v[16:17], v[38:39], v[16:17] op_sel_hi:[0,1]
	v_mul_f32_e32 v208, 0xbfb8aa3b, v10
	v_mul_f32_e32 v209, 0xbfb8aa3b, v11
	v_mul_f32_e32 v210, 0xbfb8aa3b, v12
	v_mul_f32_e32 v211, 0xbfb8aa3b, v13
	v_exp_f32_e32 v208, v208
	v_exp_f32_e32 v209, v209
	v_exp_f32_e32 v210, v210
	v_exp_f32_e32 v211, v211
	v_add_f32_e32 v208, 1.0, v208
	v_add_f32_e32 v209, 1.0, v209
	v_add_f32_e32 v210, 1.0, v210
	v_add_f32_e32 v211, 1.0, v211
	v_rcp_f32_e32 v208, v208
	v_rcp_f32_e32 v209, v209
	v_rcp_f32_e32 v210, v210
	v_rcp_f32_e32 v211, v211
	v_pk_mul_f32 v[10:11], v[10:11], v[208:209]
	v_pk_mul_f32 v[12:13], v[12:13], v[210:211]
	v_pk_mul_f32 v[10:11], v[10:11], v[232:233]
	v_pk_mul_f32 v[12:13], v[12:13], v[234:235]
	v_pk_mul_f32 v[10:11], v[38:39], v[10:11] op_sel_hi:[0,1]
	v_pk_mul_f32 v[12:13], v[38:39], v[12:13] op_sel_hi:[0,1]
	v_mul_f32_e32 v208, 0xbfb8aa3b, v6
	v_mul_f32_e32 v209, 0xbfb8aa3b, v7
	v_mul_f32_e32 v210, 0xbfb8aa3b, v8
	v_mul_f32_e32 v211, 0xbfb8aa3b, v9
	v_exp_f32_e32 v208, v208
	v_exp_f32_e32 v209, v209
	v_exp_f32_e32 v210, v210
	v_exp_f32_e32 v211, v211
	v_add_f32_e32 v208, 1.0, v208
	v_add_f32_e32 v209, 1.0, v209
	v_add_f32_e32 v210, 1.0, v210
	v_add_f32_e32 v211, 1.0, v211
	v_rcp_f32_e32 v208, v208
	v_rcp_f32_e32 v209, v209
	v_rcp_f32_e32 v210, v210
	v_rcp_f32_e32 v211, v211
	v_pk_mul_f32 v[6:7], v[6:7], v[208:209]
	v_pk_mul_f32 v[8:9], v[8:9], v[210:211]
	v_pk_mul_f32 v[6:7], v[6:7], v[236:237]
	v_pk_mul_f32 v[8:9], v[8:9], v[238:239]
	v_pk_mul_f32 v[6:7], v[38:39], v[6:7] op_sel_hi:[0,1]
	v_pk_mul_f32 v[8:9], v[38:39], v[8:9] op_sel_hi:[0,1]
	v_mul_f32_e32 v208, 0xbfb8aa3b, v2
	v_mul_f32_e32 v209, 0xbfb8aa3b, v3
	v_mul_f32_e32 v210, 0xbfb8aa3b, v4
	v_mul_f32_e32 v211, 0xbfb8aa3b, v5
	v_exp_f32_e32 v208, v208
	v_exp_f32_e32 v209, v209
	v_exp_f32_e32 v210, v210
	v_exp_f32_e32 v211, v211
	v_add_f32_e32 v208, 1.0, v208
	v_add_f32_e32 v209, 1.0, v209
	v_add_f32_e32 v210, 1.0, v210
	v_add_f32_e32 v211, 1.0, v211
	v_rcp_f32_e32 v208, v208
	v_rcp_f32_e32 v209, v209
	v_rcp_f32_e32 v210, v210
	v_rcp_f32_e32 v211, v211
	v_pk_mul_f32 v[2:3], v[2:3], v[208:209]
	v_pk_mul_f32 v[4:5], v[4:5], v[210:211]
	v_pk_mul_f32 v[2:3], v[2:3], v[240:241]
	v_pk_mul_f32 v[4:5], v[4:5], v[242:243]
	v_pk_mul_f32 v[2:3], v[38:39], v[2:3] op_sel_hi:[0,1]
	v_pk_mul_f32 v[4:5], v[38:39], v[4:5] op_sel_hi:[0,1]
	v_permlane16_swap_b32_e32 v14, v10
	v_permlane16_swap_b32_e32 v15, v11
	v_permlane16_swap_b32_e32 v16, v12
	v_permlane16_swap_b32_e32 v17, v13
	v_lshlrev_b32_e32 v208, 16, v46
	v_and_b32_e32 v209, 0xffff0000, v46
	v_lshlrev_b32_e32 v210, 16, v47
	v_and_b32_e32 v211, 0xffff0000, v47
	v_lshlrev_b32_e32 v212, 16, v48
	v_and_b32_e32 v213, 0xffff0000, v48
	v_lshlrev_b32_e32 v214, 16, v49
	v_and_b32_e32 v215, 0xffff0000, v49
	v_pk_mul_f32 v[208:209], v[208:209], v[14:15]
	v_pk_mul_f32 v[210:211], v[210:211], v[16:17]
	v_pk_mul_f32 v[212:213], v[212:213], v[10:11]
	v_pk_mul_f32 v[214:215], v[214:215], v[12:13]
	v_cvt_pk_bf16_f32 v46, v208, v209
	v_cvt_pk_bf16_f32 v47, v210, v211
	v_cvt_pk_bf16_f32 v48, v212, v213
	v_cvt_pk_bf16_f32 v49, v214, v215
	v_permlane16_swap_b32_e32 v6, v2
	v_permlane16_swap_b32_e32 v7, v3
	v_permlane16_swap_b32_e32 v8, v4
	v_permlane16_swap_b32_e32 v9, v5
	v_lshlrev_b32_e32 v208, 16, v42
	v_and_b32_e32 v209, 0xffff0000, v42
	v_lshlrev_b32_e32 v210, 16, v43
	v_and_b32_e32 v211, 0xffff0000, v43
	v_lshlrev_b32_e32 v212, 16, v44
	v_and_b32_e32 v213, 0xffff0000, v44
	v_lshlrev_b32_e32 v214, 16, v45
	v_and_b32_e32 v215, 0xffff0000, v45
	v_pk_mul_f32 v[208:209], v[208:209], v[6:7]
	v_pk_mul_f32 v[210:211], v[210:211], v[8:9]
	v_pk_mul_f32 v[212:213], v[212:213], v[2:3]
	v_pk_mul_f32 v[214:215], v[214:215], v[4:5]
	v_cvt_pk_bf16_f32 v42, v208, v209
	v_cvt_pk_bf16_f32 v43, v210, v211
	v_cvt_pk_bf16_f32 v44, v212, v213
	v_cvt_pk_bf16_f32 v45, v214, v215
	global_store_dwordx4 v154, v[46:49], s[10:11]
	global_store_dwordx4 v154, v[42:45], s[10:11] offset:256
	s_mov_b64 s[10:11], s[48:49]
	s_mov_b64 s[8:9], s[46:47]
	s_and_b64 vcc, exec, s[40:41]
	s_cbranch_vccz .LBB0_1120
	s_waitcnt vmcnt(0)
	s_cmpk_gt_u32 s19, 0xff
	s_cbranch_scc1 .LBB0_1127
	s_barrier
